# P8 final-rmsnorm and P0 XN rmsnorm loops rewritten: 4 rows in flight per wave, gain vectors hoisted, DPP wave reduction, coalesced stores
# speedup vs baseline: 1.0098x; 1.0098x over previous
.LBB0_132:
	s_and_b64 vcc, exec, s[96:97]
	s_cbranch_vccz .LBB0_137
	v_readlane_b32 s36, v249, 6
	v_readlane_b32 s37, v249, 7
	v_readlane_b32 s38, v249, 8
	v_readlane_b32 s39, v249, 9
	v_readlane_b32 s40, v249, 10
	v_readlane_b32 s41, v249, 11
	v_readlane_b32 s42, v249, 12
	v_readlane_b32 s43, v249, 13
	v_readlane_b32 s44, v249, 22
	v_readlane_b32 s45, v249, 23
	v_readlane_b32 s46, v248, 11
	v_readlane_b32 s47, v248, 12
	v_readlane_b32 s48, v248, 9
	v_readlane_b32 s49, v248, 10
	v_lshlrev_b32_e32 v1, 4, v184
	v_lshlrev_b32_e32 v2, 3, v184
	v_mov_b32_e32 v3, 0x358637bd
	s_nop 2
	global_load_dwordx4 v[6:9], v1, s[44:45] offset:0
	global_load_dwordx4 v[10:13], v1, s[44:45] offset:1024
	global_load_dwordx4 v[14:17], v1, s[44:45] offset:2048
	global_load_dwordx4 v[18:21], v1, s[44:45] offset:3072
	s_mov_b32 s0, s30
	s_mov_b32 s1, s54
	s_mov_b32 s15, s0
	s_cmp_lt_u32 s15, 0x8400
	s_cselect_b32 s12, s15, s0
	s_cmp_lt_u32 s12, 0x8000
	s_cselect_b32 s8, s36, s38
	s_cselect_b32 s9, s37, s39
	s_cselect_b32 s10, s40, s42
	s_cselect_b32 s11, s41, s43
	s_cselect_b32 s13, 0, 0x8000
	s_sub_u32 s12, s12, s13
	s_lshl_b32 s13, s12, 12
	s_add_u32 s8, s8, s13
	s_addc_u32 s9, s9, 0
	s_lshl_b32 s13, s12, 10
	s_add_u32 s10, s10, s13
	s_addc_u32 s11, s11, 0
	global_load_dwordx4 v[24:27], v1, s[8:9] offset:0
	global_load_dwordx4 v[28:31], v1, s[8:9] offset:1024
	global_load_dwordx4 v[32:35], v1, s[8:9] offset:2048
	global_load_dwordx4 v[36:39], v1, s[8:9] offset:3072
	global_load_dwordx4 v[40:43], v1, s[10:11]
	s_add_i32 s15, s15, s1
	s_cmp_lt_u32 s15, 0x8400
	s_cselect_b32 s12, s15, s0
	s_cmp_lt_u32 s12, 0x8000
	s_cselect_b32 s8, s36, s38
	s_cselect_b32 s9, s37, s39
	s_cselect_b32 s10, s40, s42
	s_cselect_b32 s11, s41, s43
	s_cselect_b32 s13, 0, 0x8000
	s_sub_u32 s12, s12, s13
	s_lshl_b32 s13, s12, 12
	s_add_u32 s8, s8, s13
	s_addc_u32 s9, s9, 0
	s_lshl_b32 s13, s12, 10
	s_add_u32 s10, s10, s13
	s_addc_u32 s11, s11, 0
	global_load_dwordx4 v[44:47], v1, s[8:9] offset:0
	global_load_dwordx4 v[48:51], v1, s[8:9] offset:1024
	global_load_dwordx4 v[52:55], v1, s[8:9] offset:2048
	global_load_dwordx4 v[56:59], v1, s[8:9] offset:3072
	global_load_dwordx4 v[60:63], v1, s[10:11]
	s_add_i32 s15, s15, s1
	s_cmp_lt_u32 s15, 0x8400
	s_cselect_b32 s12, s15, s0
	s_cmp_lt_u32 s12, 0x8000
	s_cselect_b32 s8, s36, s38
	s_cselect_b32 s9, s37, s39
	s_cselect_b32 s10, s40, s42
	s_cselect_b32 s11, s41, s43
	s_cselect_b32 s13, 0, 0x8000
	s_sub_u32 s12, s12, s13
	s_lshl_b32 s13, s12, 12
	s_add_u32 s8, s8, s13
	s_addc_u32 s9, s9, 0
	s_lshl_b32 s13, s12, 10
	s_add_u32 s10, s10, s13
	s_addc_u32 s11, s11, 0
	global_load_dwordx4 v[64:67], v1, s[8:9] offset:0
	global_load_dwordx4 v[68:71], v1, s[8:9] offset:1024
	global_load_dwordx4 v[72:75], v1, s[8:9] offset:2048
	global_load_dwordx4 v[76:79], v1, s[8:9] offset:3072
	global_load_dwordx4 v[80:83], v1, s[10:11]
	s_add_i32 s15, s15, s1
	s_cmp_lt_u32 s15, 0x8400
	s_cselect_b32 s12, s15, s0
	s_cmp_lt_u32 s12, 0x8000
	s_cselect_b32 s8, s36, s38
	s_cselect_b32 s9, s37, s39
	s_cselect_b32 s10, s40, s42
	s_cselect_b32 s11, s41, s43
	s_cselect_b32 s13, 0, 0x8000
	s_sub_u32 s12, s12, s13
	s_lshl_b32 s13, s12, 12
	s_add_u32 s8, s8, s13
	s_addc_u32 s9, s9, 0
	s_lshl_b32 s13, s12, 10
	s_add_u32 s10, s10, s13
	s_addc_u32 s11, s11, 0
	global_load_dwordx4 v[84:87], v1, s[8:9] offset:0
	global_load_dwordx4 v[88:91], v1, s[8:9] offset:1024
	global_load_dwordx4 v[92:95], v1, s[8:9] offset:2048
	global_load_dwordx4 v[96:99], v1, s[8:9] offset:3072
	global_load_dwordx4 v[100:103], v1, s[10:11]
	s_add_i32 s15, s15, s1
	s_mul_i32 s8, s1, 3
	s_add_i32 s8, s8, s0
	s_cmp_lt_u32 s8, 0x8400
	s_cbranch_scc0 .Lxn_tail
	s_mov_b32 s14, s0
	s_waitcnt vmcnt(15)
	v_mul_f32_e32 v4, v24, v24
	v_mul_f32_e32 v5, v25, v25
	v_fmac_f32_e32 v4, v26, v26
	v_fmac_f32_e32 v5, v27, v27
	v_fmac_f32_e32 v4, v28, v28
	v_fmac_f32_e32 v5, v29, v29
	v_fmac_f32_e32 v4, v30, v30
	v_fmac_f32_e32 v5, v31, v31
	v_fmac_f32_e32 v4, v32, v32
	v_fmac_f32_e32 v5, v33, v33
	v_fmac_f32_e32 v4, v34, v34
	v_fmac_f32_e32 v5, v35, v35
	v_fmac_f32_e32 v4, v36, v36
	v_fmac_f32_e32 v5, v37, v37
	v_fmac_f32_e32 v4, v38, v38
	v_fmac_f32_e32 v5, v39, v39
	v_add_f32_e32 v4, v4, v5
	v_cvt_pk_bf16_f32 v112, v40, v41
	v_cvt_pk_bf16_f32 v113, v42, v43
	v_add_f32_dpp v4, v4, v4 quad_perm:[1,0,3,2] row_mask:0xf bank_mask:0xf
	s_nop 1
	v_add_f32_dpp v4, v4, v4 quad_perm:[2,3,0,1] row_mask:0xf bank_mask:0xf
	s_nop 1
	v_add_f32_dpp v4, v4, v4 row_half_mirror row_mask:0xf bank_mask:0xf
	s_nop 1
	v_add_f32_dpp v4, v4, v4 row_mirror row_mask:0xf bank_mask:0xf
	s_nop 1
	v_readlane_b32 s28, v4, 0
	v_readlane_b32 s29, v4, 16
	v_readlane_b32 s50, v4, 32
	v_readlane_b32 s51, v4, 48
	s_lshl_b32 s13, s14, 11
	s_add_u32 s16, s46, s13
	s_addc_u32 s17, s47, 0
	s_lshl_b32 s13, s14, 9
	s_add_u32 s18, s48, s13
	s_addc_u32 s19, s49, 0
	v_mov_b32_e32 v114, s28
	v_add_f32_e32 v114, s29, v114
	v_add_f32_e32 v114, s50, v114
	v_add_f32_e32 v114, s51, v114
	v_fmamk_f32 v114, v114, 0x3a800000, v3
	v_rsq_f32_e32 v114, v114
	s_nop 0
	v_pk_mul_f32 v[116:117], v[24:25], v[114:115] op_sel_hi:[1,0]
	v_pk_mul_f32 v[118:119], v[26:27], v[114:115] op_sel_hi:[1,0]
	v_pk_mul_f32 v[120:121], v[28:29], v[114:115] op_sel_hi:[1,0]
	v_pk_mul_f32 v[122:123], v[30:31], v[114:115] op_sel_hi:[1,0]
	v_pk_mul_f32 v[124:125], v[32:33], v[114:115] op_sel_hi:[1,0]
	v_pk_mul_f32 v[126:127], v[34:35], v[114:115] op_sel_hi:[1,0]
	v_pk_mul_f32 v[128:129], v[36:37], v[114:115] op_sel_hi:[1,0]
	v_pk_mul_f32 v[130:131], v[38:39], v[114:115] op_sel_hi:[1,0]
	v_pk_mul_f32 v[116:117], v[6:7], v[116:117]
	v_pk_mul_f32 v[118:119], v[8:9], v[118:119]
	v_pk_mul_f32 v[120:121], v[10:11], v[120:121]
	v_pk_mul_f32 v[122:123], v[12:13], v[122:123]
	v_pk_mul_f32 v[124:125], v[14:15], v[124:125]
	v_pk_mul_f32 v[126:127], v[16:17], v[126:127]
	v_pk_mul_f32 v[128:129], v[18:19], v[128:129]
	v_pk_mul_f32 v[130:131], v[20:21], v[130:131]
	v_cvt_pk_bf16_f32 v104, v116, v117
	v_cvt_pk_bf16_f32 v105, v118, v119
	v_cvt_pk_bf16_f32 v106, v120, v121
	v_cvt_pk_bf16_f32 v107, v122, v123
	v_cvt_pk_bf16_f32 v108, v124, v125
	v_cvt_pk_bf16_f32 v109, v126, v127
	v_cvt_pk_bf16_f32 v110, v128, v129
	v_cvt_pk_bf16_f32 v111, v130, v131
	global_store_dwordx2 v2, v[104:105], s[16:17] offset:0
	global_store_dwordx2 v2, v[106:107], s[16:17] offset:512
	global_store_dwordx2 v2, v[108:109], s[16:17] offset:1024
	global_store_dwordx2 v2, v[110:111], s[16:17] offset:1536
	global_store_dwordx2 v2, v[112:113], s[18:19]
	s_cmp_lt_u32 s15, 0x8400
	s_cselect_b32 s12, s15, s0
	s_cmp_lt_u32 s12, 0x8000
	s_cselect_b32 s8, s36, s38
	s_cselect_b32 s9, s37, s39
	s_cselect_b32 s10, s40, s42
	s_cselect_b32 s11, s41, s43
	s_cselect_b32 s13, 0, 0x8000
	s_sub_u32 s12, s12, s13
	s_lshl_b32 s13, s12, 12
	s_add_u32 s8, s8, s13
	s_addc_u32 s9, s9, 0
	s_lshl_b32 s13, s12, 10
	s_add_u32 s10, s10, s13
	s_addc_u32 s11, s11, 0
	global_load_dwordx4 v[24:27], v1, s[8:9] offset:0
	global_load_dwordx4 v[28:31], v1, s[8:9] offset:1024
	global_load_dwordx4 v[32:35], v1, s[8:9] offset:2048
	global_load_dwordx4 v[36:39], v1, s[8:9] offset:3072
	global_load_dwordx4 v[40:43], v1, s[10:11]
	s_add_i32 s15, s15, s1
	s_add_i32 s14, s14, s1
	s_waitcnt vmcnt(20)
	v_mul_f32_e32 v4, v44, v44
	v_mul_f32_e32 v5, v45, v45
	v_fmac_f32_e32 v4, v46, v46
	v_fmac_f32_e32 v5, v47, v47
	v_fmac_f32_e32 v4, v48, v48
	v_fmac_f32_e32 v5, v49, v49
	v_fmac_f32_e32 v4, v50, v50
	v_fmac_f32_e32 v5, v51, v51
	v_fmac_f32_e32 v4, v52, v52
	v_fmac_f32_e32 v5, v53, v53
	v_fmac_f32_e32 v4, v54, v54
	v_fmac_f32_e32 v5, v55, v55
	v_fmac_f32_e32 v4, v56, v56
	v_fmac_f32_e32 v5, v57, v57
	v_fmac_f32_e32 v4, v58, v58
	v_fmac_f32_e32 v5, v59, v59
	v_add_f32_e32 v4, v4, v5
	v_cvt_pk_bf16_f32 v112, v60, v61
	v_cvt_pk_bf16_f32 v113, v62, v63
	v_add_f32_dpp v4, v4, v4 quad_perm:[1,0,3,2] row_mask:0xf bank_mask:0xf
	s_nop 1
	v_add_f32_dpp v4, v4, v4 quad_perm:[2,3,0,1] row_mask:0xf bank_mask:0xf
	s_nop 1
	v_add_f32_dpp v4, v4, v4 row_half_mirror row_mask:0xf bank_mask:0xf
	s_nop 1
	v_add_f32_dpp v4, v4, v4 row_mirror row_mask:0xf bank_mask:0xf
	s_nop 1
	v_readlane_b32 s28, v4, 0
	v_readlane_b32 s29, v4, 16
	v_readlane_b32 s50, v4, 32
	v_readlane_b32 s51, v4, 48
	s_lshl_b32 s13, s14, 11
	s_add_u32 s16, s46, s13
	s_addc_u32 s17, s47, 0
	s_lshl_b32 s13, s14, 9
	s_add_u32 s18, s48, s13
	s_addc_u32 s19, s49, 0
	v_mov_b32_e32 v114, s28
	v_add_f32_e32 v114, s29, v114
	v_add_f32_e32 v114, s50, v114
	v_add_f32_e32 v114, s51, v114
	v_fmamk_f32 v114, v114, 0x3a800000, v3
	v_rsq_f32_e32 v114, v114
	s_nop 0
	v_pk_mul_f32 v[116:117], v[44:45], v[114:115] op_sel_hi:[1,0]
	v_pk_mul_f32 v[118:119], v[46:47], v[114:115] op_sel_hi:[1,0]
	v_pk_mul_f32 v[120:121], v[48:49], v[114:115] op_sel_hi:[1,0]
	v_pk_mul_f32 v[122:123], v[50:51], v[114:115] op_sel_hi:[1,0]
	v_pk_mul_f32 v[124:125], v[52:53], v[114:115] op_sel_hi:[1,0]
	v_pk_mul_f32 v[126:127], v[54:55], v[114:115] op_sel_hi:[1,0]
	v_pk_mul_f32 v[128:129], v[56:57], v[114:115] op_sel_hi:[1,0]
	v_pk_mul_f32 v[130:131], v[58:59], v[114:115] op_sel_hi:[1,0]
	v_pk_mul_f32 v[116:117], v[6:7], v[116:117]
	v_pk_mul_f32 v[118:119], v[8:9], v[118:119]
	v_pk_mul_f32 v[120:121], v[10:11], v[120:121]
	v_pk_mul_f32 v[122:123], v[12:13], v[122:123]
	v_pk_mul_f32 v[124:125], v[14:15], v[124:125]
	v_pk_mul_f32 v[126:127], v[16:17], v[126:127]
	v_pk_mul_f32 v[128:129], v[18:19], v[128:129]
	v_pk_mul_f32 v[130:131], v[20:21], v[130:131]
	v_cvt_pk_bf16_f32 v104, v116, v117
	v_cvt_pk_bf16_f32 v105, v118, v119
	v_cvt_pk_bf16_f32 v106, v120, v121
	v_cvt_pk_bf16_f32 v107, v122, v123
	v_cvt_pk_bf16_f32 v108, v124, v125
	v_cvt_pk_bf16_f32 v109, v126, v127
	v_cvt_pk_bf16_f32 v110, v128, v129
	v_cvt_pk_bf16_f32 v111, v130, v131
	global_store_dwordx2 v2, v[104:105], s[16:17] offset:0
	global_store_dwordx2 v2, v[106:107], s[16:17] offset:512
	global_store_dwordx2 v2, v[108:109], s[16:17] offset:1024
	global_store_dwordx2 v2, v[110:111], s[16:17] offset:1536
	global_store_dwordx2 v2, v[112:113], s[18:19]
	s_cmp_lt_u32 s15, 0x8400
	s_cselect_b32 s12, s15, s0
	s_cmp_lt_u32 s12, 0x8000
	s_cselect_b32 s8, s36, s38
	s_cselect_b32 s9, s37, s39
	s_cselect_b32 s10, s40, s42
	s_cselect_b32 s11, s41, s43
	s_cselect_b32 s13, 0, 0x8000
	s_sub_u32 s12, s12, s13
	s_lshl_b32 s13, s12, 12
	s_add_u32 s8, s8, s13
	s_addc_u32 s9, s9, 0
	s_lshl_b32 s13, s12, 10
	s_add_u32 s10, s10, s13
	s_addc_u32 s11, s11, 0
	global_load_dwordx4 v[44:47], v1, s[8:9] offset:0
	global_load_dwordx4 v[48:51], v1, s[8:9] offset:1024
	global_load_dwordx4 v[52:55], v1, s[8:9] offset:2048
	global_load_dwordx4 v[56:59], v1, s[8:9] offset:3072
	global_load_dwordx4 v[60:63], v1, s[10:11]
	s_add_i32 s15, s15, s1
	s_add_i32 s14, s14, s1
	s_waitcnt vmcnt(25)
	v_mul_f32_e32 v4, v64, v64
	v_mul_f32_e32 v5, v65, v65
	v_fmac_f32_e32 v4, v66, v66
	v_fmac_f32_e32 v5, v67, v67
	v_fmac_f32_e32 v4, v68, v68
	v_fmac_f32_e32 v5, v69, v69
	v_fmac_f32_e32 v4, v70, v70
	v_fmac_f32_e32 v5, v71, v71
	v_fmac_f32_e32 v4, v72, v72
	v_fmac_f32_e32 v5, v73, v73
	v_fmac_f32_e32 v4, v74, v74
	v_fmac_f32_e32 v5, v75, v75
	v_fmac_f32_e32 v4, v76, v76
	v_fmac_f32_e32 v5, v77, v77
	v_fmac_f32_e32 v4, v78, v78
	v_fmac_f32_e32 v5, v79, v79
	v_add_f32_e32 v4, v4, v5
	v_cvt_pk_bf16_f32 v112, v80, v81
	v_cvt_pk_bf16_f32 v113, v82, v83
	v_add_f32_dpp v4, v4, v4 quad_perm:[1,0,3,2] row_mask:0xf bank_mask:0xf
	s_nop 1
	v_add_f32_dpp v4, v4, v4 quad_perm:[2,3,0,1] row_mask:0xf bank_mask:0xf
	s_nop 1
	v_add_f32_dpp v4, v4, v4 row_half_mirror row_mask:0xf bank_mask:0xf
	s_nop 1
	v_add_f32_dpp v4, v4, v4 row_mirror row_mask:0xf bank_mask:0xf
	s_nop 1
	v_readlane_b32 s28, v4, 0
	v_readlane_b32 s29, v4, 16
	v_readlane_b32 s50, v4, 32
	v_readlane_b32 s51, v4, 48
	s_lshl_b32 s13, s14, 11
	s_add_u32 s16, s46, s13
	s_addc_u32 s17, s47, 0
	s_lshl_b32 s13, s14, 9
	s_add_u32 s18, s48, s13
	s_addc_u32 s19, s49, 0
	v_mov_b32_e32 v114, s28
	v_add_f32_e32 v114, s29, v114
	v_add_f32_e32 v114, s50, v114
	v_add_f32_e32 v114, s51, v114
	v_fmamk_f32 v114, v114, 0x3a800000, v3
	v_rsq_f32_e32 v114, v114
	s_nop 0
	v_pk_mul_f32 v[116:117], v[64:65], v[114:115] op_sel_hi:[1,0]
	v_pk_mul_f32 v[118:119], v[66:67], v[114:115] op_sel_hi:[1,0]
	v_pk_mul_f32 v[120:121], v[68:69], v[114:115] op_sel_hi:[1,0]
	v_pk_mul_f32 v[122:123], v[70:71], v[114:115] op_sel_hi:[1,0]
	v_pk_mul_f32 v[124:125], v[72:73], v[114:115] op_sel_hi:[1,0]
	v_pk_mul_f32 v[126:127], v[74:75], v[114:115] op_sel_hi:[1,0]
	v_pk_mul_f32 v[128:129], v[76:77], v[114:115] op_sel_hi:[1,0]
	v_pk_mul_f32 v[130:131], v[78:79], v[114:115] op_sel_hi:[1,0]
	v_pk_mul_f32 v[116:117], v[6:7], v[116:117]
	v_pk_mul_f32 v[118:119], v[8:9], v[118:119]
	v_pk_mul_f32 v[120:121], v[10:11], v[120:121]
	v_pk_mul_f32 v[122:123], v[12:13], v[122:123]
	v_pk_mul_f32 v[124:125], v[14:15], v[124:125]
	v_pk_mul_f32 v[126:127], v[16:17], v[126:127]
	v_pk_mul_f32 v[128:129], v[18:19], v[128:129]
	v_pk_mul_f32 v[130:131], v[20:21], v[130:131]
	v_cvt_pk_bf16_f32 v104, v116, v117
	v_cvt_pk_bf16_f32 v105, v118, v119
	v_cvt_pk_bf16_f32 v106, v120, v121
	v_cvt_pk_bf16_f32 v107, v122, v123
	v_cvt_pk_bf16_f32 v108, v124, v125
	v_cvt_pk_bf16_f32 v109, v126, v127
	v_cvt_pk_bf16_f32 v110, v128, v129
	v_cvt_pk_bf16_f32 v111, v130, v131
	global_store_dwordx2 v2, v[104:105], s[16:17] offset:0
	global_store_dwordx2 v2, v[106:107], s[16:17] offset:512
	global_store_dwordx2 v2, v[108:109], s[16:17] offset:1024
	global_store_dwordx2 v2, v[110:111], s[16:17] offset:1536
	global_store_dwordx2 v2, v[112:113], s[18:19]
	s_cmp_lt_u32 s15, 0x8400
	s_cselect_b32 s12, s15, s0
	s_cmp_lt_u32 s12, 0x8000
	s_cselect_b32 s8, s36, s38
	s_cselect_b32 s9, s37, s39
	s_cselect_b32 s10, s40, s42
	s_cselect_b32 s11, s41, s43
	s_cselect_b32 s13, 0, 0x8000
	s_sub_u32 s12, s12, s13
	s_lshl_b32 s13, s12, 12
	s_add_u32 s8, s8, s13
	s_addc_u32 s9, s9, 0
	s_lshl_b32 s13, s12, 10
	s_add_u32 s10, s10, s13
	s_addc_u32 s11, s11, 0
	global_load_dwordx4 v[64:67], v1, s[8:9] offset:0
	global_load_dwordx4 v[68:71], v1, s[8:9] offset:1024
	global_load_dwordx4 v[72:75], v1, s[8:9] offset:2048
	global_load_dwordx4 v[76:79], v1, s[8:9] offset:3072
	global_load_dwordx4 v[80:83], v1, s[10:11]
	s_add_i32 s15, s15, s1
	s_add_i32 s14, s14, s1
	s_waitcnt vmcnt(30)
	v_mul_f32_e32 v4, v84, v84
	v_mul_f32_e32 v5, v85, v85
	v_fmac_f32_e32 v4, v86, v86
	v_fmac_f32_e32 v5, v87, v87
	v_fmac_f32_e32 v4, v88, v88
	v_fmac_f32_e32 v5, v89, v89
	v_fmac_f32_e32 v4, v90, v90
	v_fmac_f32_e32 v5, v91, v91
	v_fmac_f32_e32 v4, v92, v92
	v_fmac_f32_e32 v5, v93, v93
	v_fmac_f32_e32 v4, v94, v94
	v_fmac_f32_e32 v5, v95, v95
	v_fmac_f32_e32 v4, v96, v96
	v_fmac_f32_e32 v5, v97, v97
	v_fmac_f32_e32 v4, v98, v98
	v_fmac_f32_e32 v5, v99, v99
	v_add_f32_e32 v4, v4, v5
	v_cvt_pk_bf16_f32 v112, v100, v101
	v_cvt_pk_bf16_f32 v113, v102, v103
	v_add_f32_dpp v4, v4, v4 quad_perm:[1,0,3,2] row_mask:0xf bank_mask:0xf
	s_nop 1
	v_add_f32_dpp v4, v4, v4 quad_perm:[2,3,0,1] row_mask:0xf bank_mask:0xf
	s_nop 1
	v_add_f32_dpp v4, v4, v4 row_half_mirror row_mask:0xf bank_mask:0xf
	s_nop 1
	v_add_f32_dpp v4, v4, v4 row_mirror row_mask:0xf bank_mask:0xf
	s_nop 1
	v_readlane_b32 s28, v4, 0
	v_readlane_b32 s29, v4, 16
	v_readlane_b32 s50, v4, 32
	v_readlane_b32 s51, v4, 48
	s_lshl_b32 s13, s14, 11
	s_add_u32 s16, s46, s13
	s_addc_u32 s17, s47, 0
	s_lshl_b32 s13, s14, 9
	s_add_u32 s18, s48, s13
	s_addc_u32 s19, s49, 0
	v_mov_b32_e32 v114, s28
	v_add_f32_e32 v114, s29, v114
	v_add_f32_e32 v114, s50, v114
	v_add_f32_e32 v114, s51, v114
	v_fmamk_f32 v114, v114, 0x3a800000, v3
	v_rsq_f32_e32 v114, v114
	s_nop 0
	v_pk_mul_f32 v[116:117], v[84:85], v[114:115] op_sel_hi:[1,0]
	v_pk_mul_f32 v[118:119], v[86:87], v[114:115] op_sel_hi:[1,0]
	v_pk_mul_f32 v[120:121], v[88:89], v[114:115] op_sel_hi:[1,0]
	v_pk_mul_f32 v[122:123], v[90:91], v[114:115] op_sel_hi:[1,0]
	v_pk_mul_f32 v[124:125], v[92:93], v[114:115] op_sel_hi:[1,0]
	v_pk_mul_f32 v[126:127], v[94:95], v[114:115] op_sel_hi:[1,0]
	v_pk_mul_f32 v[128:129], v[96:97], v[114:115] op_sel_hi:[1,0]
	v_pk_mul_f32 v[130:131], v[98:99], v[114:115] op_sel_hi:[1,0]
	v_pk_mul_f32 v[116:117], v[6:7], v[116:117]
	v_pk_mul_f32 v[118:119], v[8:9], v[118:119]
	v_pk_mul_f32 v[120:121], v[10:11], v[120:121]
	v_pk_mul_f32 v[122:123], v[12:13], v[122:123]
	v_pk_mul_f32 v[124:125], v[14:15], v[124:125]
	v_pk_mul_f32 v[126:127], v[16:17], v[126:127]
	v_pk_mul_f32 v[128:129], v[18:19], v[128:129]
	v_pk_mul_f32 v[130:131], v[20:21], v[130:131]
	v_cvt_pk_bf16_f32 v104, v116, v117
	v_cvt_pk_bf16_f32 v105, v118, v119
	v_cvt_pk_bf16_f32 v106, v120, v121
	v_cvt_pk_bf16_f32 v107, v122, v123
	v_cvt_pk_bf16_f32 v108, v124, v125
	v_cvt_pk_bf16_f32 v109, v126, v127
	v_cvt_pk_bf16_f32 v110, v128, v129
	v_cvt_pk_bf16_f32 v111, v130, v131
	global_store_dwordx2 v2, v[104:105], s[16:17] offset:0
	global_store_dwordx2 v2, v[106:107], s[16:17] offset:512
	global_store_dwordx2 v2, v[108:109], s[16:17] offset:1024
	global_store_dwordx2 v2, v[110:111], s[16:17] offset:1536
	global_store_dwordx2 v2, v[112:113], s[18:19]
	s_cmp_lt_u32 s15, 0x8400
	s_cselect_b32 s12, s15, s0
	s_cmp_lt_u32 s12, 0x8000
	s_cselect_b32 s8, s36, s38
	s_cselect_b32 s9, s37, s39
	s_cselect_b32 s10, s40, s42
	s_cselect_b32 s11, s41, s43
	s_cselect_b32 s13, 0, 0x8000
	s_sub_u32 s12, s12, s13
	s_lshl_b32 s13, s12, 12
	s_add_u32 s8, s8, s13
	s_addc_u32 s9, s9, 0
	s_lshl_b32 s13, s12, 10
	s_add_u32 s10, s10, s13
	s_addc_u32 s11, s11, 0
	global_load_dwordx4 v[84:87], v1, s[8:9] offset:0
	global_load_dwordx4 v[88:91], v1, s[8:9] offset:1024
	global_load_dwordx4 v[92:95], v1, s[8:9] offset:2048
	global_load_dwordx4 v[96:99], v1, s[8:9] offset:3072
	global_load_dwordx4 v[100:103], v1, s[10:11]
	s_add_i32 s15, s15, s1
	s_add_i32 s14, s14, s1
	s_mov_b32 s0, s14
.Lxn_loop:
	s_mul_i32 s8, s1, 3
	s_add_i32 s8, s8, s0
	s_cmp_lt_u32 s8, 0x8400
	s_cbranch_scc0 .Lxn_tail
	s_waitcnt vmcnt(30)
	v_mul_f32_e32 v4, v24, v24
	v_mul_f32_e32 v5, v25, v25
	v_fmac_f32_e32 v4, v26, v26
	v_fmac_f32_e32 v5, v27, v27
	v_fmac_f32_e32 v4, v28, v28
	v_fmac_f32_e32 v5, v29, v29
	v_fmac_f32_e32 v4, v30, v30
	v_fmac_f32_e32 v5, v31, v31
	v_fmac_f32_e32 v4, v32, v32
	v_fmac_f32_e32 v5, v33, v33
	v_fmac_f32_e32 v4, v34, v34
	v_fmac_f32_e32 v5, v35, v35
	v_fmac_f32_e32 v4, v36, v36
	v_fmac_f32_e32 v5, v37, v37
	v_fmac_f32_e32 v4, v38, v38
	v_fmac_f32_e32 v5, v39, v39
	v_add_f32_e32 v4, v4, v5
	v_cvt_pk_bf16_f32 v112, v40, v41
	v_cvt_pk_bf16_f32 v113, v42, v43
	v_add_f32_dpp v4, v4, v4 quad_perm:[1,0,3,2] row_mask:0xf bank_mask:0xf
	s_nop 1
	v_add_f32_dpp v4, v4, v4 quad_perm:[2,3,0,1] row_mask:0xf bank_mask:0xf
	s_nop 1
	v_add_f32_dpp v4, v4, v4 row_half_mirror row_mask:0xf bank_mask:0xf
	s_nop 1
	v_add_f32_dpp v4, v4, v4 row_mirror row_mask:0xf bank_mask:0xf
	s_nop 1
	v_readlane_b32 s28, v4, 0
	v_readlane_b32 s29, v4, 16
	v_readlane_b32 s50, v4, 32
	v_readlane_b32 s51, v4, 48
	s_lshl_b32 s13, s14, 11
	s_add_u32 s16, s46, s13
	s_addc_u32 s17, s47, 0
	s_lshl_b32 s13, s14, 9
	s_add_u32 s18, s48, s13
	s_addc_u32 s19, s49, 0
	v_mov_b32_e32 v114, s28
	v_add_f32_e32 v114, s29, v114
	v_add_f32_e32 v114, s50, v114
	v_add_f32_e32 v114, s51, v114
	v_fmamk_f32 v114, v114, 0x3a800000, v3
	v_rsq_f32_e32 v114, v114
	s_nop 0
	v_pk_mul_f32 v[116:117], v[24:25], v[114:115] op_sel_hi:[1,0]
	v_pk_mul_f32 v[118:119], v[26:27], v[114:115] op_sel_hi:[1,0]
	v_pk_mul_f32 v[120:121], v[28:29], v[114:115] op_sel_hi:[1,0]
	v_pk_mul_f32 v[122:123], v[30:31], v[114:115] op_sel_hi:[1,0]
	v_pk_mul_f32 v[124:125], v[32:33], v[114:115] op_sel_hi:[1,0]
	v_pk_mul_f32 v[126:127], v[34:35], v[114:115] op_sel_hi:[1,0]
	v_pk_mul_f32 v[128:129], v[36:37], v[114:115] op_sel_hi:[1,0]
	v_pk_mul_f32 v[130:131], v[38:39], v[114:115] op_sel_hi:[1,0]
	v_pk_mul_f32 v[116:117], v[6:7], v[116:117]
	v_pk_mul_f32 v[118:119], v[8:9], v[118:119]
	v_pk_mul_f32 v[120:121], v[10:11], v[120:121]
	v_pk_mul_f32 v[122:123], v[12:13], v[122:123]
	v_pk_mul_f32 v[124:125], v[14:15], v[124:125]
	v_pk_mul_f32 v[126:127], v[16:17], v[126:127]
	v_pk_mul_f32 v[128:129], v[18:19], v[128:129]
	v_pk_mul_f32 v[130:131], v[20:21], v[130:131]
	v_cvt_pk_bf16_f32 v104, v116, v117
	v_cvt_pk_bf16_f32 v105, v118, v119
	v_cvt_pk_bf16_f32 v106, v120, v121
	v_cvt_pk_bf16_f32 v107, v122, v123
	v_cvt_pk_bf16_f32 v108, v124, v125
	v_cvt_pk_bf16_f32 v109, v126, v127
	v_cvt_pk_bf16_f32 v110, v128, v129
	v_cvt_pk_bf16_f32 v111, v130, v131
	global_store_dwordx2 v2, v[104:105], s[16:17] offset:0
	global_store_dwordx2 v2, v[106:107], s[16:17] offset:512
	global_store_dwordx2 v2, v[108:109], s[16:17] offset:1024
	global_store_dwordx2 v2, v[110:111], s[16:17] offset:1536
	global_store_dwordx2 v2, v[112:113], s[18:19]
	s_cmp_lt_u32 s15, 0x8400
	s_cselect_b32 s12, s15, s0
	s_cmp_lt_u32 s12, 0x8000
	s_cselect_b32 s8, s36, s38
	s_cselect_b32 s9, s37, s39
	s_cselect_b32 s10, s40, s42
	s_cselect_b32 s11, s41, s43
	s_cselect_b32 s13, 0, 0x8000
	s_sub_u32 s12, s12, s13
	s_lshl_b32 s13, s12, 12
	s_add_u32 s8, s8, s13
	s_addc_u32 s9, s9, 0
	s_lshl_b32 s13, s12, 10
	s_add_u32 s10, s10, s13
	s_addc_u32 s11, s11, 0
	global_load_dwordx4 v[24:27], v1, s[8:9] offset:0
	global_load_dwordx4 v[28:31], v1, s[8:9] offset:1024
	global_load_dwordx4 v[32:35], v1, s[8:9] offset:2048
	global_load_dwordx4 v[36:39], v1, s[8:9] offset:3072
	global_load_dwordx4 v[40:43], v1, s[10:11]
	s_add_i32 s15, s15, s1
	s_add_i32 s14, s14, s1
	s_waitcnt vmcnt(30)
	v_mul_f32_e32 v4, v44, v44
	v_mul_f32_e32 v5, v45, v45
	v_fmac_f32_e32 v4, v46, v46
	v_fmac_f32_e32 v5, v47, v47
	v_fmac_f32_e32 v4, v48, v48
	v_fmac_f32_e32 v5, v49, v49
	v_fmac_f32_e32 v4, v50, v50
	v_fmac_f32_e32 v5, v51, v51
	v_fmac_f32_e32 v4, v52, v52
	v_fmac_f32_e32 v5, v53, v53
	v_fmac_f32_e32 v4, v54, v54
	v_fmac_f32_e32 v5, v55, v55
	v_fmac_f32_e32 v4, v56, v56
	v_fmac_f32_e32 v5, v57, v57
	v_fmac_f32_e32 v4, v58, v58
	v_fmac_f32_e32 v5, v59, v59
	v_add_f32_e32 v4, v4, v5
	v_cvt_pk_bf16_f32 v112, v60, v61
	v_cvt_pk_bf16_f32 v113, v62, v63
	v_add_f32_dpp v4, v4, v4 quad_perm:[1,0,3,2] row_mask:0xf bank_mask:0xf
	s_nop 1
	v_add_f32_dpp v4, v4, v4 quad_perm:[2,3,0,1] row_mask:0xf bank_mask:0xf
	s_nop 1
	v_add_f32_dpp v4, v4, v4 row_half_mirror row_mask:0xf bank_mask:0xf
	s_nop 1
	v_add_f32_dpp v4, v4, v4 row_mirror row_mask:0xf bank_mask:0xf
	s_nop 1
	v_readlane_b32 s28, v4, 0
	v_readlane_b32 s29, v4, 16
	v_readlane_b32 s50, v4, 32
	v_readlane_b32 s51, v4, 48
	s_lshl_b32 s13, s14, 11
	s_add_u32 s16, s46, s13
	s_addc_u32 s17, s47, 0
	s_lshl_b32 s13, s14, 9
	s_add_u32 s18, s48, s13
	s_addc_u32 s19, s49, 0
	v_mov_b32_e32 v114, s28
	v_add_f32_e32 v114, s29, v114
	v_add_f32_e32 v114, s50, v114
	v_add_f32_e32 v114, s51, v114
	v_fmamk_f32 v114, v114, 0x3a800000, v3
	v_rsq_f32_e32 v114, v114
	s_nop 0
	v_pk_mul_f32 v[116:117], v[44:45], v[114:115] op_sel_hi:[1,0]
	v_pk_mul_f32 v[118:119], v[46:47], v[114:115] op_sel_hi:[1,0]
	v_pk_mul_f32 v[120:121], v[48:49], v[114:115] op_sel_hi:[1,0]
	v_pk_mul_f32 v[122:123], v[50:51], v[114:115] op_sel_hi:[1,0]
	v_pk_mul_f32 v[124:125], v[52:53], v[114:115] op_sel_hi:[1,0]
	v_pk_mul_f32 v[126:127], v[54:55], v[114:115] op_sel_hi:[1,0]
	v_pk_mul_f32 v[128:129], v[56:57], v[114:115] op_sel_hi:[1,0]
	v_pk_mul_f32 v[130:131], v[58:59], v[114:115] op_sel_hi:[1,0]
	v_pk_mul_f32 v[116:117], v[6:7], v[116:117]
	v_pk_mul_f32 v[118:119], v[8:9], v[118:119]
	v_pk_mul_f32 v[120:121], v[10:11], v[120:121]
	v_pk_mul_f32 v[122:123], v[12:13], v[122:123]
	v_pk_mul_f32 v[124:125], v[14:15], v[124:125]
	v_pk_mul_f32 v[126:127], v[16:17], v[126:127]
	v_pk_mul_f32 v[128:129], v[18:19], v[128:129]
	v_pk_mul_f32 v[130:131], v[20:21], v[130:131]
	v_cvt_pk_bf16_f32 v104, v116, v117
	v_cvt_pk_bf16_f32 v105, v118, v119
	v_cvt_pk_bf16_f32 v106, v120, v121
	v_cvt_pk_bf16_f32 v107, v122, v123
	v_cvt_pk_bf16_f32 v108, v124, v125
	v_cvt_pk_bf16_f32 v109, v126, v127
	v_cvt_pk_bf16_f32 v110, v128, v129
	v_cvt_pk_bf16_f32 v111, v130, v131
	global_store_dwordx2 v2, v[104:105], s[16:17] offset:0
	global_store_dwordx2 v2, v[106:107], s[16:17] offset:512
	global_store_dwordx2 v2, v[108:109], s[16:17] offset:1024
	global_store_dwordx2 v2, v[110:111], s[16:17] offset:1536
	global_store_dwordx2 v2, v[112:113], s[18:19]
	s_cmp_lt_u32 s15, 0x8400
	s_cselect_b32 s12, s15, s0
	s_cmp_lt_u32 s12, 0x8000
	s_cselect_b32 s8, s36, s38
	s_cselect_b32 s9, s37, s39
	s_cselect_b32 s10, s40, s42
	s_cselect_b32 s11, s41, s43
	s_cselect_b32 s13, 0, 0x8000
	s_sub_u32 s12, s12, s13
	s_lshl_b32 s13, s12, 12
	s_add_u32 s8, s8, s13
	s_addc_u32 s9, s9, 0
	s_lshl_b32 s13, s12, 10
	s_add_u32 s10, s10, s13
	s_addc_u32 s11, s11, 0
	global_load_dwordx4 v[44:47], v1, s[8:9] offset:0
	global_load_dwordx4 v[48:51], v1, s[8:9] offset:1024
	global_load_dwordx4 v[52:55], v1, s[8:9] offset:2048
	global_load_dwordx4 v[56:59], v1, s[8:9] offset:3072
	global_load_dwordx4 v[60:63], v1, s[10:11]
	s_add_i32 s15, s15, s1
	s_add_i32 s14, s14, s1
	s_waitcnt vmcnt(30)
	v_mul_f32_e32 v4, v64, v64
	v_mul_f32_e32 v5, v65, v65
	v_fmac_f32_e32 v4, v66, v66
	v_fmac_f32_e32 v5, v67, v67
	v_fmac_f32_e32 v4, v68, v68
	v_fmac_f32_e32 v5, v69, v69
	v_fmac_f32_e32 v4, v70, v70
	v_fmac_f32_e32 v5, v71, v71
	v_fmac_f32_e32 v4, v72, v72
	v_fmac_f32_e32 v5, v73, v73
	v_fmac_f32_e32 v4, v74, v74
	v_fmac_f32_e32 v5, v75, v75
	v_fmac_f32_e32 v4, v76, v76
	v_fmac_f32_e32 v5, v77, v77
	v_fmac_f32_e32 v4, v78, v78
	v_fmac_f32_e32 v5, v79, v79
	v_add_f32_e32 v4, v4, v5
	v_cvt_pk_bf16_f32 v112, v80, v81
	v_cvt_pk_bf16_f32 v113, v82, v83
	v_add_f32_dpp v4, v4, v4 quad_perm:[1,0,3,2] row_mask:0xf bank_mask:0xf
	s_nop 1
	v_add_f32_dpp v4, v4, v4 quad_perm:[2,3,0,1] row_mask:0xf bank_mask:0xf
	s_nop 1
	v_add_f32_dpp v4, v4, v4 row_half_mirror row_mask:0xf bank_mask:0xf
	s_nop 1
	v_add_f32_dpp v4, v4, v4 row_mirror row_mask:0xf bank_mask:0xf
	s_nop 1
	v_readlane_b32 s28, v4, 0
	v_readlane_b32 s29, v4, 16
	v_readlane_b32 s50, v4, 32
	v_readlane_b32 s51, v4, 48
	s_lshl_b32 s13, s14, 11
	s_add_u32 s16, s46, s13
	s_addc_u32 s17, s47, 0
	s_lshl_b32 s13, s14, 9
	s_add_u32 s18, s48, s13
	s_addc_u32 s19, s49, 0
	v_mov_b32_e32 v114, s28
	v_add_f32_e32 v114, s29, v114
	v_add_f32_e32 v114, s50, v114
	v_add_f32_e32 v114, s51, v114
	v_fmamk_f32 v114, v114, 0x3a800000, v3
	v_rsq_f32_e32 v114, v114
	s_nop 0
	v_pk_mul_f32 v[116:117], v[64:65], v[114:115] op_sel_hi:[1,0]
	v_pk_mul_f32 v[118:119], v[66:67], v[114:115] op_sel_hi:[1,0]
	v_pk_mul_f32 v[120:121], v[68:69], v[114:115] op_sel_hi:[1,0]
	v_pk_mul_f32 v[122:123], v[70:71], v[114:115] op_sel_hi:[1,0]
	v_pk_mul_f32 v[124:125], v[72:73], v[114:115] op_sel_hi:[1,0]
	v_pk_mul_f32 v[126:127], v[74:75], v[114:115] op_sel_hi:[1,0]
	v_pk_mul_f32 v[128:129], v[76:77], v[114:115] op_sel_hi:[1,0]
	v_pk_mul_f32 v[130:131], v[78:79], v[114:115] op_sel_hi:[1,0]
	v_pk_mul_f32 v[116:117], v[6:7], v[116:117]
	v_pk_mul_f32 v[118:119], v[8:9], v[118:119]
	v_pk_mul_f32 v[120:121], v[10:11], v[120:121]
	v_pk_mul_f32 v[122:123], v[12:13], v[122:123]
	v_pk_mul_f32 v[124:125], v[14:15], v[124:125]
	v_pk_mul_f32 v[126:127], v[16:17], v[126:127]
	v_pk_mul_f32 v[128:129], v[18:19], v[128:129]
	v_pk_mul_f32 v[130:131], v[20:21], v[130:131]
	v_cvt_pk_bf16_f32 v104, v116, v117
	v_cvt_pk_bf16_f32 v105, v118, v119
	v_cvt_pk_bf16_f32 v106, v120, v121
	v_cvt_pk_bf16_f32 v107, v122, v123
	v_cvt_pk_bf16_f32 v108, v124, v125
	v_cvt_pk_bf16_f32 v109, v126, v127
	v_cvt_pk_bf16_f32 v110, v128, v129
	v_cvt_pk_bf16_f32 v111, v130, v131
	global_store_dwordx2 v2, v[104:105], s[16:17] offset:0
	global_store_dwordx2 v2, v[106:107], s[16:17] offset:512
	global_store_dwordx2 v2, v[108:109], s[16:17] offset:1024
	global_store_dwordx2 v2, v[110:111], s[16:17] offset:1536
	global_store_dwordx2 v2, v[112:113], s[18:19]
	s_cmp_lt_u32 s15, 0x8400
	s_cselect_b32 s12, s15, s0
	s_cmp_lt_u32 s12, 0x8000
	s_cselect_b32 s8, s36, s38
	s_cselect_b32 s9, s37, s39
	s_cselect_b32 s10, s40, s42
	s_cselect_b32 s11, s41, s43
	s_cselect_b32 s13, 0, 0x8000
	s_sub_u32 s12, s12, s13
	s_lshl_b32 s13, s12, 12
	s_add_u32 s8, s8, s13
	s_addc_u32 s9, s9, 0
	s_lshl_b32 s13, s12, 10
	s_add_u32 s10, s10, s13
	s_addc_u32 s11, s11, 0
	global_load_dwordx4 v[64:67], v1, s[8:9] offset:0
	global_load_dwordx4 v[68:71], v1, s[8:9] offset:1024
	global_load_dwordx4 v[72:75], v1, s[8:9] offset:2048
	global_load_dwordx4 v[76:79], v1, s[8:9] offset:3072
	global_load_dwordx4 v[80:83], v1, s[10:11]
	s_add_i32 s15, s15, s1
	s_add_i32 s14, s14, s1
	s_waitcnt vmcnt(30)
	v_mul_f32_e32 v4, v84, v84
	v_mul_f32_e32 v5, v85, v85
	v_fmac_f32_e32 v4, v86, v86
	v_fmac_f32_e32 v5, v87, v87
	v_fmac_f32_e32 v4, v88, v88
	v_fmac_f32_e32 v5, v89, v89
	v_fmac_f32_e32 v4, v90, v90
	v_fmac_f32_e32 v5, v91, v91
	v_fmac_f32_e32 v4, v92, v92
	v_fmac_f32_e32 v5, v93, v93
	v_fmac_f32_e32 v4, v94, v94
	v_fmac_f32_e32 v5, v95, v95
	v_fmac_f32_e32 v4, v96, v96
	v_fmac_f32_e32 v5, v97, v97
	v_fmac_f32_e32 v4, v98, v98
	v_fmac_f32_e32 v5, v99, v99
	v_add_f32_e32 v4, v4, v5
	v_cvt_pk_bf16_f32 v112, v100, v101
	v_cvt_pk_bf16_f32 v113, v102, v103
	v_add_f32_dpp v4, v4, v4 quad_perm:[1,0,3,2] row_mask:0xf bank_mask:0xf
	s_nop 1
	v_add_f32_dpp v4, v4, v4 quad_perm:[2,3,0,1] row_mask:0xf bank_mask:0xf
	s_nop 1
	v_add_f32_dpp v4, v4, v4 row_half_mirror row_mask:0xf bank_mask:0xf
	s_nop 1
	v_add_f32_dpp v4, v4, v4 row_mirror row_mask:0xf bank_mask:0xf
	s_nop 1
	v_readlane_b32 s28, v4, 0
	v_readlane_b32 s29, v4, 16
	v_readlane_b32 s50, v4, 32
	v_readlane_b32 s51, v4, 48
	s_lshl_b32 s13, s14, 11
	s_add_u32 s16, s46, s13
	s_addc_u32 s17, s47, 0
	s_lshl_b32 s13, s14, 9
	s_add_u32 s18, s48, s13
	s_addc_u32 s19, s49, 0
	v_mov_b32_e32 v114, s28
	v_add_f32_e32 v114, s29, v114
	v_add_f32_e32 v114, s50, v114
	v_add_f32_e32 v114, s51, v114
	v_fmamk_f32 v114, v114, 0x3a800000, v3
	v_rsq_f32_e32 v114, v114
	s_nop 0
	v_pk_mul_f32 v[116:117], v[84:85], v[114:115] op_sel_hi:[1,0]
	v_pk_mul_f32 v[118:119], v[86:87], v[114:115] op_sel_hi:[1,0]
	v_pk_mul_f32 v[120:121], v[88:89], v[114:115] op_sel_hi:[1,0]
	v_pk_mul_f32 v[122:123], v[90:91], v[114:115] op_sel_hi:[1,0]
	v_pk_mul_f32 v[124:125], v[92:93], v[114:115] op_sel_hi:[1,0]
	v_pk_mul_f32 v[126:127], v[94:95], v[114:115] op_sel_hi:[1,0]
	v_pk_mul_f32 v[128:129], v[96:97], v[114:115] op_sel_hi:[1,0]
	v_pk_mul_f32 v[130:131], v[98:99], v[114:115] op_sel_hi:[1,0]
	v_pk_mul_f32 v[116:117], v[6:7], v[116:117]
	v_pk_mul_f32 v[118:119], v[8:9], v[118:119]
	v_pk_mul_f32 v[120:121], v[10:11], v[120:121]
	v_pk_mul_f32 v[122:123], v[12:13], v[122:123]
	v_pk_mul_f32 v[124:125], v[14:15], v[124:125]
	v_pk_mul_f32 v[126:127], v[16:17], v[126:127]
	v_pk_mul_f32 v[128:129], v[18:19], v[128:129]
	v_pk_mul_f32 v[130:131], v[20:21], v[130:131]
	v_cvt_pk_bf16_f32 v104, v116, v117
	v_cvt_pk_bf16_f32 v105, v118, v119
	v_cvt_pk_bf16_f32 v106, v120, v121
	v_cvt_pk_bf16_f32 v107, v122, v123
	v_cvt_pk_bf16_f32 v108, v124, v125
	v_cvt_pk_bf16_f32 v109, v126, v127
	v_cvt_pk_bf16_f32 v110, v128, v129
	v_cvt_pk_bf16_f32 v111, v130, v131
	global_store_dwordx2 v2, v[104:105], s[16:17] offset:0
	global_store_dwordx2 v2, v[106:107], s[16:17] offset:512
	global_store_dwordx2 v2, v[108:109], s[16:17] offset:1024
	global_store_dwordx2 v2, v[110:111], s[16:17] offset:1536
	global_store_dwordx2 v2, v[112:113], s[18:19]
	s_cmp_lt_u32 s15, 0x8400
	s_cselect_b32 s12, s15, s0
	s_cmp_lt_u32 s12, 0x8000
	s_cselect_b32 s8, s36, s38
	s_cselect_b32 s9, s37, s39
	s_cselect_b32 s10, s40, s42
	s_cselect_b32 s11, s41, s43
	s_cselect_b32 s13, 0, 0x8000
	s_sub_u32 s12, s12, s13
	s_lshl_b32 s13, s12, 12
	s_add_u32 s8, s8, s13
	s_addc_u32 s9, s9, 0
	s_lshl_b32 s13, s12, 10
	s_add_u32 s10, s10, s13
	s_addc_u32 s11, s11, 0
	global_load_dwordx4 v[84:87], v1, s[8:9] offset:0
	global_load_dwordx4 v[88:91], v1, s[8:9] offset:1024
	global_load_dwordx4 v[92:95], v1, s[8:9] offset:2048
	global_load_dwordx4 v[96:99], v1, s[8:9] offset:3072
	global_load_dwordx4 v[100:103], v1, s[10:11]
	s_add_i32 s15, s15, s1
	s_add_i32 s14, s14, s1
	s_mov_b32 s0, s14
	s_branch .Lxn_loop
.Lxn_tail:
	s_waitcnt vmcnt(0)
	s_mov_b32 s14, s0
	s_cmp_lt_u32 s14, 0x8400
	s_cbranch_scc0 .Lxn_done
	v_mul_f32_e32 v4, v24, v24
	v_mul_f32_e32 v5, v25, v25
	v_fmac_f32_e32 v4, v26, v26
	v_fmac_f32_e32 v5, v27, v27
	v_fmac_f32_e32 v4, v28, v28
	v_fmac_f32_e32 v5, v29, v29
	v_fmac_f32_e32 v4, v30, v30
	v_fmac_f32_e32 v5, v31, v31
	v_fmac_f32_e32 v4, v32, v32
	v_fmac_f32_e32 v5, v33, v33
	v_fmac_f32_e32 v4, v34, v34
	v_fmac_f32_e32 v5, v35, v35
	v_fmac_f32_e32 v4, v36, v36
	v_fmac_f32_e32 v5, v37, v37
	v_fmac_f32_e32 v4, v38, v38
	v_fmac_f32_e32 v5, v39, v39
	v_add_f32_e32 v4, v4, v5
	v_cvt_pk_bf16_f32 v112, v40, v41
	v_cvt_pk_bf16_f32 v113, v42, v43
	v_add_f32_dpp v4, v4, v4 quad_perm:[1,0,3,2] row_mask:0xf bank_mask:0xf
	s_nop 1
	v_add_f32_dpp v4, v4, v4 quad_perm:[2,3,0,1] row_mask:0xf bank_mask:0xf
	s_nop 1
	v_add_f32_dpp v4, v4, v4 row_half_mirror row_mask:0xf bank_mask:0xf
	s_nop 1
	v_add_f32_dpp v4, v4, v4 row_mirror row_mask:0xf bank_mask:0xf
	s_nop 1
	v_readlane_b32 s28, v4, 0
	v_readlane_b32 s29, v4, 16
	v_readlane_b32 s50, v4, 32
	v_readlane_b32 s51, v4, 48
	s_lshl_b32 s13, s14, 11
	s_add_u32 s16, s46, s13
	s_addc_u32 s17, s47, 0
	s_lshl_b32 s13, s14, 9
	s_add_u32 s18, s48, s13
	s_addc_u32 s19, s49, 0
	v_mov_b32_e32 v114, s28
	v_add_f32_e32 v114, s29, v114
	v_add_f32_e32 v114, s50, v114
	v_add_f32_e32 v114, s51, v114
	v_fmamk_f32 v114, v114, 0x3a800000, v3
	v_rsq_f32_e32 v114, v114
	s_nop 0
	v_pk_mul_f32 v[116:117], v[24:25], v[114:115] op_sel_hi:[1,0]
	v_pk_mul_f32 v[118:119], v[26:27], v[114:115] op_sel_hi:[1,0]
	v_pk_mul_f32 v[120:121], v[28:29], v[114:115] op_sel_hi:[1,0]
	v_pk_mul_f32 v[122:123], v[30:31], v[114:115] op_sel_hi:[1,0]
	v_pk_mul_f32 v[124:125], v[32:33], v[114:115] op_sel_hi:[1,0]
	v_pk_mul_f32 v[126:127], v[34:35], v[114:115] op_sel_hi:[1,0]
	v_pk_mul_f32 v[128:129], v[36:37], v[114:115] op_sel_hi:[1,0]
	v_pk_mul_f32 v[130:131], v[38:39], v[114:115] op_sel_hi:[1,0]
	v_pk_mul_f32 v[116:117], v[6:7], v[116:117]
	v_pk_mul_f32 v[118:119], v[8:9], v[118:119]
	v_pk_mul_f32 v[120:121], v[10:11], v[120:121]
	v_pk_mul_f32 v[122:123], v[12:13], v[122:123]
	v_pk_mul_f32 v[124:125], v[14:15], v[124:125]
	v_pk_mul_f32 v[126:127], v[16:17], v[126:127]
	v_pk_mul_f32 v[128:129], v[18:19], v[128:129]
	v_pk_mul_f32 v[130:131], v[20:21], v[130:131]
	v_cvt_pk_bf16_f32 v104, v116, v117
	v_cvt_pk_bf16_f32 v105, v118, v119
	v_cvt_pk_bf16_f32 v106, v120, v121
	v_cvt_pk_bf16_f32 v107, v122, v123
	v_cvt_pk_bf16_f32 v108, v124, v125
	v_cvt_pk_bf16_f32 v109, v126, v127
	v_cvt_pk_bf16_f32 v110, v128, v129
	v_cvt_pk_bf16_f32 v111, v130, v131
	global_store_dwordx2 v2, v[104:105], s[16:17] offset:0
	global_store_dwordx2 v2, v[106:107], s[16:17] offset:512
	global_store_dwordx2 v2, v[108:109], s[16:17] offset:1024
	global_store_dwordx2 v2, v[110:111], s[16:17] offset:1536
	global_store_dwordx2 v2, v[112:113], s[18:19]
	s_add_i32 s14, s14, s1
	s_cmp_lt_u32 s14, 0x8400
	s_cbranch_scc0 .Lxn_done
	v_mul_f32_e32 v4, v44, v44
	v_mul_f32_e32 v5, v45, v45
	v_fmac_f32_e32 v4, v46, v46
	v_fmac_f32_e32 v5, v47, v47
	v_fmac_f32_e32 v4, v48, v48
	v_fmac_f32_e32 v5, v49, v49
	v_fmac_f32_e32 v4, v50, v50
	v_fmac_f32_e32 v5, v51, v51
	v_fmac_f32_e32 v4, v52, v52
	v_fmac_f32_e32 v5, v53, v53
	v_fmac_f32_e32 v4, v54, v54
	v_fmac_f32_e32 v5, v55, v55
	v_fmac_f32_e32 v4, v56, v56
	v_fmac_f32_e32 v5, v57, v57
	v_fmac_f32_e32 v4, v58, v58
	v_fmac_f32_e32 v5, v59, v59
	v_add_f32_e32 v4, v4, v5
	v_cvt_pk_bf16_f32 v112, v60, v61
	v_cvt_pk_bf16_f32 v113, v62, v63
	v_add_f32_dpp v4, v4, v4 quad_perm:[1,0,3,2] row_mask:0xf bank_mask:0xf
	s_nop 1
	v_add_f32_dpp v4, v4, v4 quad_perm:[2,3,0,1] row_mask:0xf bank_mask:0xf
	s_nop 1
	v_add_f32_dpp v4, v4, v4 row_half_mirror row_mask:0xf bank_mask:0xf
	s_nop 1
	v_add_f32_dpp v4, v4, v4 row_mirror row_mask:0xf bank_mask:0xf
	s_nop 1
	v_readlane_b32 s28, v4, 0
	v_readlane_b32 s29, v4, 16
	v_readlane_b32 s50, v4, 32
	v_readlane_b32 s51, v4, 48
	s_lshl_b32 s13, s14, 11
	s_add_u32 s16, s46, s13
	s_addc_u32 s17, s47, 0
	s_lshl_b32 s13, s14, 9
	s_add_u32 s18, s48, s13
	s_addc_u32 s19, s49, 0
	v_mov_b32_e32 v114, s28
	v_add_f32_e32 v114, s29, v114
	v_add_f32_e32 v114, s50, v114
	v_add_f32_e32 v114, s51, v114
	v_fmamk_f32 v114, v114, 0x3a800000, v3
	v_rsq_f32_e32 v114, v114
	s_nop 0
	v_pk_mul_f32 v[116:117], v[44:45], v[114:115] op_sel_hi:[1,0]
	v_pk_mul_f32 v[118:119], v[46:47], v[114:115] op_sel_hi:[1,0]
	v_pk_mul_f32 v[120:121], v[48:49], v[114:115] op_sel_hi:[1,0]
	v_pk_mul_f32 v[122:123], v[50:51], v[114:115] op_sel_hi:[1,0]
	v_pk_mul_f32 v[124:125], v[52:53], v[114:115] op_sel_hi:[1,0]
	v_pk_mul_f32 v[126:127], v[54:55], v[114:115] op_sel_hi:[1,0]
	v_pk_mul_f32 v[128:129], v[56:57], v[114:115] op_sel_hi:[1,0]
	v_pk_mul_f32 v[130:131], v[58:59], v[114:115] op_sel_hi:[1,0]
	v_pk_mul_f32 v[116:117], v[6:7], v[116:117]
	v_pk_mul_f32 v[118:119], v[8:9], v[118:119]
	v_pk_mul_f32 v[120:121], v[10:11], v[120:121]
	v_pk_mul_f32 v[122:123], v[12:13], v[122:123]
	v_pk_mul_f32 v[124:125], v[14:15], v[124:125]
	v_pk_mul_f32 v[126:127], v[16:17], v[126:127]
	v_pk_mul_f32 v[128:129], v[18:19], v[128:129]
	v_pk_mul_f32 v[130:131], v[20:21], v[130:131]
	v_cvt_pk_bf16_f32 v104, v116, v117
	v_cvt_pk_bf16_f32 v105, v118, v119
	v_cvt_pk_bf16_f32 v106, v120, v121
	v_cvt_pk_bf16_f32 v107, v122, v123
	v_cvt_pk_bf16_f32 v108, v124, v125
	v_cvt_pk_bf16_f32 v109, v126, v127
	v_cvt_pk_bf16_f32 v110, v128, v129
	v_cvt_pk_bf16_f32 v111, v130, v131
	global_store_dwordx2 v2, v[104:105], s[16:17] offset:0
	global_store_dwordx2 v2, v[106:107], s[16:17] offset:512
	global_store_dwordx2 v2, v[108:109], s[16:17] offset:1024
	global_store_dwordx2 v2, v[110:111], s[16:17] offset:1536
	global_store_dwordx2 v2, v[112:113], s[18:19]
	s_add_i32 s14, s14, s1
	s_cmp_lt_u32 s14, 0x8400
	s_cbranch_scc0 .Lxn_done
	v_mul_f32_e32 v4, v64, v64
	v_mul_f32_e32 v5, v65, v65
	v_fmac_f32_e32 v4, v66, v66
	v_fmac_f32_e32 v5, v67, v67
	v_fmac_f32_e32 v4, v68, v68
	v_fmac_f32_e32 v5, v69, v69
	v_fmac_f32_e32 v4, v70, v70
	v_fmac_f32_e32 v5, v71, v71
	v_fmac_f32_e32 v4, v72, v72
	v_fmac_f32_e32 v5, v73, v73
	v_fmac_f32_e32 v4, v74, v74
	v_fmac_f32_e32 v5, v75, v75
	v_fmac_f32_e32 v4, v76, v76
	v_fmac_f32_e32 v5, v77, v77
	v_fmac_f32_e32 v4, v78, v78
	v_fmac_f32_e32 v5, v79, v79
	v_add_f32_e32 v4, v4, v5
	v_cvt_pk_bf16_f32 v112, v80, v81
	v_cvt_pk_bf16_f32 v113, v82, v83
	v_add_f32_dpp v4, v4, v4 quad_perm:[1,0,3,2] row_mask:0xf bank_mask:0xf
	s_nop 1
	v_add_f32_dpp v4, v4, v4 quad_perm:[2,3,0,1] row_mask:0xf bank_mask:0xf
	s_nop 1
	v_add_f32_dpp v4, v4, v4 row_half_mirror row_mask:0xf bank_mask:0xf
	s_nop 1
	v_add_f32_dpp v4, v4, v4 row_mirror row_mask:0xf bank_mask:0xf
	s_nop 1
	v_readlane_b32 s28, v4, 0
	v_readlane_b32 s29, v4, 16
	v_readlane_b32 s50, v4, 32
	v_readlane_b32 s51, v4, 48
	s_lshl_b32 s13, s14, 11
	s_add_u32 s16, s46, s13
	s_addc_u32 s17, s47, 0
	s_lshl_b32 s13, s14, 9
	s_add_u32 s18, s48, s13
	s_addc_u32 s19, s49, 0
	v_mov_b32_e32 v114, s28
	v_add_f32_e32 v114, s29, v114
	v_add_f32_e32 v114, s50, v114
	v_add_f32_e32 v114, s51, v114
	v_fmamk_f32 v114, v114, 0x3a800000, v3
	v_rsq_f32_e32 v114, v114
	s_nop 0
	v_pk_mul_f32 v[116:117], v[64:65], v[114:115] op_sel_hi:[1,0]
	v_pk_mul_f32 v[118:119], v[66:67], v[114:115] op_sel_hi:[1,0]
	v_pk_mul_f32 v[120:121], v[68:69], v[114:115] op_sel_hi:[1,0]
	v_pk_mul_f32 v[122:123], v[70:71], v[114:115] op_sel_hi:[1,0]
	v_pk_mul_f32 v[124:125], v[72:73], v[114:115] op_sel_hi:[1,0]
	v_pk_mul_f32 v[126:127], v[74:75], v[114:115] op_sel_hi:[1,0]
	v_pk_mul_f32 v[128:129], v[76:77], v[114:115] op_sel_hi:[1,0]
	v_pk_mul_f32 v[130:131], v[78:79], v[114:115] op_sel_hi:[1,0]
	v_pk_mul_f32 v[116:117], v[6:7], v[116:117]
	v_pk_mul_f32 v[118:119], v[8:9], v[118:119]
	v_pk_mul_f32 v[120:121], v[10:11], v[120:121]
	v_pk_mul_f32 v[122:123], v[12:13], v[122:123]
	v_pk_mul_f32 v[124:125], v[14:15], v[124:125]
	v_pk_mul_f32 v[126:127], v[16:17], v[126:127]
	v_pk_mul_f32 v[128:129], v[18:19], v[128:129]
	v_pk_mul_f32 v[130:131], v[20:21], v[130:131]
	v_cvt_pk_bf16_f32 v104, v116, v117
	v_cvt_pk_bf16_f32 v105, v118, v119
	v_cvt_pk_bf16_f32 v106, v120, v121
	v_cvt_pk_bf16_f32 v107, v122, v123
	v_cvt_pk_bf16_f32 v108, v124, v125
	v_cvt_pk_bf16_f32 v109, v126, v127
	v_cvt_pk_bf16_f32 v110, v128, v129
	v_cvt_pk_bf16_f32 v111, v130, v131
	global_store_dwordx2 v2, v[104:105], s[16:17] offset:0
	global_store_dwordx2 v2, v[106:107], s[16:17] offset:512
	global_store_dwordx2 v2, v[108:109], s[16:17] offset:1024
	global_store_dwordx2 v2, v[110:111], s[16:17] offset:1536
	global_store_dwordx2 v2, v[112:113], s[18:19]
	s_add_i32 s14, s14, s1
.Lxn_done:
.LBB0_137:
	s_cmpk_gt_i32 s30, 0x3fff
	s_cbranch_scc1 .LBB0_140
	s_ashr_i32 s31, s30, 31
	v_readlane_b32 s36, v249, 6
	s_lshl_b64 s[0:1], s[30:31], 11
	v_readlane_b32 s44, v249, 14
	v_lshlrev_b32_e32 v2, 1, v0
	v_readlane_b32 s45, v249, 15
	s_add_u32 s0, s44, s0
	v_ashrrev_i32_e32 v3, 31, v2
	s_addc_u32 s1, s45, s1
	s_ashr_i32 s55, s54, 31
	v_lshl_add_u64 v[2:3], v[2:3], 4, s[0:1]
	s_lshl_b64 s[0:1], s[54:55], 11
	s_lshl_b64 s[8:9], s[30:31], 10
	s_add_u32 s8, s24, s8
	v_ashrrev_i32_e32 v1, 31, v0
	s_addc_u32 s9, s25, s9
	v_lshl_add_u64 v[0:1], v[0:1], 4, s[8:9]
	s_mov_b64 s[8:9], 0x139c5000
	v_lshl_add_u64 v[2:3], v[2:3], 0, 16
	v_lshl_add_u64 v[0:1], v[0:1], 0, s[8:9]
	s_lshl_b64 s[8:9], s[54:55], 10
	s_mov_b32 s3, s30
	v_readlane_b32 s37, v249, 7
	v_readlane_b32 s38, v249, 8
	v_readlane_b32 s39, v249, 9
	v_readlane_b32 s40, v249, 10
	v_readlane_b32 s41, v249, 11
	v_readlane_b32 s42, v249, 12
	v_readlane_b32 s43, v249, 13
	v_readlane_b32 s46, v249, 16
	v_readlane_b32 s47, v249, 17
	v_readlane_b32 s48, v249, 18
	v_readlane_b32 s49, v249, 19
	v_readlane_b32 s50, v249, 20
	v_readlane_b32 s51, v249, 21

.LBB0_1208:
	s_cmp_lt_i32 s26, 9
	s_cselect_b64 s[2:3], -1, 0
	s_and_b64 s[0:1], s[2:3], s[0:1]
	s_andn2_b64 vcc, exec, s[0:1]
	s_cbranch_vccnz .LBB0_1214
	s_andn2_b64 vcc, exec, s[60:61]
	s_cbranch_vccnz .LBB0_1214
	v_lshlrev_b32_e32 v0, 3, v184
	v_lshlrev_b32_e32 v1, 4, v184
	v_mov_b32_e32 v2, 0x358637bd
	global_load_dwordx4 v[4:7], v1, s[20:21] offset:0
	global_load_dwordx4 v[8:11], v1, s[20:21] offset:1024
	global_load_dwordx4 v[12:15], v1, s[20:21] offset:2048
	global_load_dwordx4 v[16:19], v1, s[20:21] offset:3072
	s_mov_b32 s0, s30
	s_mov_b32 s1, s70
	s_mov_b32 s9, s0
	s_cmp_lt_u32 s9, 0x8400
	s_cselect_b32 s8, s9, s0
	s_lshl_b32 s8, s8, 11
	s_add_u32 s2, s12, s8
	s_addc_u32 s3, s13, 0
	global_load_dwordx2 v[20:21], v0, s[2:3] offset:0
	global_load_dwordx2 v[22:23], v0, s[2:3] offset:512
	global_load_dwordx2 v[24:25], v0, s[2:3] offset:1024
	global_load_dwordx2 v[26:27], v0, s[2:3] offset:1536
	s_add_i32 s9, s9, s1
	s_cmp_lt_u32 s9, 0x8400
	s_cselect_b32 s8, s9, s0
	s_lshl_b32 s8, s8, 11
	s_add_u32 s2, s12, s8
	s_addc_u32 s3, s13, 0
	global_load_dwordx2 v[28:29], v0, s[2:3] offset:0
	global_load_dwordx2 v[30:31], v0, s[2:3] offset:512
	global_load_dwordx2 v[32:33], v0, s[2:3] offset:1024
	global_load_dwordx2 v[34:35], v0, s[2:3] offset:1536
	s_add_i32 s9, s9, s1
	s_cmp_lt_u32 s9, 0x8400
	s_cselect_b32 s8, s9, s0
	s_lshl_b32 s8, s8, 11
	s_add_u32 s2, s12, s8
	s_addc_u32 s3, s13, 0
	global_load_dwordx2 v[36:37], v0, s[2:3] offset:0
	global_load_dwordx2 v[38:39], v0, s[2:3] offset:512
	global_load_dwordx2 v[40:41], v0, s[2:3] offset:1024
	global_load_dwordx2 v[42:43], v0, s[2:3] offset:1536
	s_add_i32 s9, s9, s1
	s_cmp_lt_u32 s9, 0x8400
	s_cselect_b32 s8, s9, s0
	s_lshl_b32 s8, s8, 11
	s_add_u32 s2, s12, s8
	s_addc_u32 s3, s13, 0
	global_load_dwordx2 v[44:45], v0, s[2:3] offset:0
	global_load_dwordx2 v[46:47], v0, s[2:3] offset:512
	global_load_dwordx2 v[48:49], v0, s[2:3] offset:1024
	global_load_dwordx2 v[50:51], v0, s[2:3] offset:1536
	s_add_i32 s9, s9, s1
	s_mul_i32 s8, s1, 3
	s_add_i32 s8, s8, s0
	s_cmp_lt_u32 s8, 0x8400
	s_cbranch_scc0 .Lp8_tail
	s_mov_b32 s14, s0
	s_waitcnt vmcnt(12)
	s_nop 1
	v_lshlrev_b32_e32 v52, 16, v20
	v_and_b32_e32 v53, 0xffff0000, v20
	v_lshlrev_b32_e32 v54, 16, v21
	v_and_b32_e32 v55, 0xffff0000, v21
	v_lshlrev_b32_e32 v56, 16, v22
	v_and_b32_e32 v57, 0xffff0000, v22
	v_lshlrev_b32_e32 v58, 16, v23
	v_and_b32_e32 v59, 0xffff0000, v23
	v_lshlrev_b32_e32 v60, 16, v24
	v_and_b32_e32 v61, 0xffff0000, v24
	v_lshlrev_b32_e32 v62, 16, v25
	v_and_b32_e32 v63, 0xffff0000, v25
	v_lshlrev_b32_e32 v64, 16, v26
	v_and_b32_e32 v65, 0xffff0000, v26
	v_lshlrev_b32_e32 v66, 16, v27
	v_and_b32_e32 v67, 0xffff0000, v27
	s_cmp_lt_u32 s9, 0x8400
	s_cselect_b32 s8, s9, s0
	s_lshl_b32 s8, s8, 11
	s_add_u32 s2, s12, s8
	s_addc_u32 s3, s13, 0
	global_load_dwordx2 v[20:21], v0, s[2:3] offset:0
	global_load_dwordx2 v[22:23], v0, s[2:3] offset:512
	global_load_dwordx2 v[24:25], v0, s[2:3] offset:1024
	global_load_dwordx2 v[26:27], v0, s[2:3] offset:1536
	s_add_i32 s9, s9, s1
	v_mul_f32_e32 v3, v52, v52
	v_mul_f32_e32 v70, v53, v53
	v_fmac_f32_e32 v3, v54, v54
	v_fmac_f32_e32 v70, v55, v55
	v_fmac_f32_e32 v3, v56, v56
	v_fmac_f32_e32 v70, v57, v57
	v_fmac_f32_e32 v3, v58, v58
	v_fmac_f32_e32 v70, v59, v59
	v_fmac_f32_e32 v3, v60, v60
	v_fmac_f32_e32 v70, v61, v61
	v_fmac_f32_e32 v3, v62, v62
	v_fmac_f32_e32 v70, v63, v63
	v_fmac_f32_e32 v3, v64, v64
	v_fmac_f32_e32 v70, v65, v65
	v_fmac_f32_e32 v3, v66, v66
	v_fmac_f32_e32 v70, v67, v67
	v_add_f32_e32 v3, v3, v70
	s_nop 1
	v_add_f32_dpp v3, v3, v3 quad_perm:[1,0,3,2] row_mask:0xf bank_mask:0xf
	s_nop 1
	v_add_f32_dpp v3, v3, v3 quad_perm:[2,3,0,1] row_mask:0xf bank_mask:0xf
	s_nop 1
	v_add_f32_dpp v3, v3, v3 row_half_mirror row_mask:0xf bank_mask:0xf
	s_nop 1
	v_add_f32_dpp v3, v3, v3 row_mirror row_mask:0xf bank_mask:0xf
	s_nop 1
	v_readlane_b32 s4, v3, 0
	v_readlane_b32 s5, v3, 16
	v_readlane_b32 s6, v3, 32
	v_readlane_b32 s7, v3, 48
	s_lshl_b32 s8, s14, 12
	s_add_u32 s10, s22, s8
	s_addc_u32 s11, s23, 0
	v_mov_b32_e32 v68, s4
	v_add_f32_e32 v68, s5, v68
	v_add_f32_e32 v68, s6, v68
	v_add_f32_e32 v68, s7, v68
	v_fmamk_f32 v68, v68, 0x3a800000, v2
	v_rsq_f32_e32 v68, v68
	s_nop 0
	v_pk_mul_f32 v[52:53], v[68:69], v[52:53] op_sel_hi:[0,1]
	v_pk_mul_f32 v[54:55], v[68:69], v[54:55] op_sel_hi:[0,1]
	v_pk_mul_f32 v[56:57], v[68:69], v[56:57] op_sel_hi:[0,1]
	v_pk_mul_f32 v[58:59], v[68:69], v[58:59] op_sel_hi:[0,1]
	v_pk_mul_f32 v[60:61], v[68:69], v[60:61] op_sel_hi:[0,1]
	v_pk_mul_f32 v[62:63], v[68:69], v[62:63] op_sel_hi:[0,1]
	v_pk_mul_f32 v[64:65], v[68:69], v[64:65] op_sel_hi:[0,1]
	v_pk_mul_f32 v[66:67], v[68:69], v[66:67] op_sel_hi:[0,1]
	v_pk_mul_f32 v[52:53], v[52:53], v[4:5]
	v_pk_mul_f32 v[54:55], v[54:55], v[6:7]
	v_pk_mul_f32 v[56:57], v[56:57], v[8:9]
	v_pk_mul_f32 v[58:59], v[58:59], v[10:11]
	v_pk_mul_f32 v[60:61], v[60:61], v[12:13]
	v_pk_mul_f32 v[62:63], v[62:63], v[14:15]
	v_pk_mul_f32 v[64:65], v[64:65], v[16:17]
	v_pk_mul_f32 v[66:67], v[66:67], v[18:19]
	global_store_dwordx4 v1, v[52:55], s[10:11] offset:0
	global_store_dwordx4 v1, v[56:59], s[10:11] offset:1024
	global_store_dwordx4 v1, v[60:63], s[10:11] offset:2048
	global_store_dwordx4 v1, v[64:67], s[10:11] offset:3072
	s_add_i32 s14, s14, s1
	s_waitcnt vmcnt(16)
	s_nop 1
	v_lshlrev_b32_e32 v52, 16, v28
	v_and_b32_e32 v53, 0xffff0000, v28
	v_lshlrev_b32_e32 v54, 16, v29
	v_and_b32_e32 v55, 0xffff0000, v29
	v_lshlrev_b32_e32 v56, 16, v30
	v_and_b32_e32 v57, 0xffff0000, v30
	v_lshlrev_b32_e32 v58, 16, v31
	v_and_b32_e32 v59, 0xffff0000, v31
	v_lshlrev_b32_e32 v60, 16, v32
	v_and_b32_e32 v61, 0xffff0000, v32
	v_lshlrev_b32_e32 v62, 16, v33
	v_and_b32_e32 v63, 0xffff0000, v33
	v_lshlrev_b32_e32 v64, 16, v34
	v_and_b32_e32 v65, 0xffff0000, v34
	v_lshlrev_b32_e32 v66, 16, v35
	v_and_b32_e32 v67, 0xffff0000, v35
	s_cmp_lt_u32 s9, 0x8400
	s_cselect_b32 s8, s9, s0
	s_lshl_b32 s8, s8, 11
	s_add_u32 s2, s12, s8
	s_addc_u32 s3, s13, 0
	global_load_dwordx2 v[28:29], v0, s[2:3] offset:0
	global_load_dwordx2 v[30:31], v0, s[2:3] offset:512
	global_load_dwordx2 v[32:33], v0, s[2:3] offset:1024
	global_load_dwordx2 v[34:35], v0, s[2:3] offset:1536
	s_add_i32 s9, s9, s1
	v_mul_f32_e32 v3, v52, v52
	v_mul_f32_e32 v70, v53, v53
	v_fmac_f32_e32 v3, v54, v54
	v_fmac_f32_e32 v70, v55, v55
	v_fmac_f32_e32 v3, v56, v56
	v_fmac_f32_e32 v70, v57, v57
	v_fmac_f32_e32 v3, v58, v58
	v_fmac_f32_e32 v70, v59, v59
	v_fmac_f32_e32 v3, v60, v60
	v_fmac_f32_e32 v70, v61, v61
	v_fmac_f32_e32 v3, v62, v62
	v_fmac_f32_e32 v70, v63, v63
	v_fmac_f32_e32 v3, v64, v64
	v_fmac_f32_e32 v70, v65, v65
	v_fmac_f32_e32 v3, v66, v66
	v_fmac_f32_e32 v70, v67, v67
	v_add_f32_e32 v3, v3, v70
	s_nop 1
	v_add_f32_dpp v3, v3, v3 quad_perm:[1,0,3,2] row_mask:0xf bank_mask:0xf
	s_nop 1
	v_add_f32_dpp v3, v3, v3 quad_perm:[2,3,0,1] row_mask:0xf bank_mask:0xf
	s_nop 1
	v_add_f32_dpp v3, v3, v3 row_half_mirror row_mask:0xf bank_mask:0xf
	s_nop 1
	v_add_f32_dpp v3, v3, v3 row_mirror row_mask:0xf bank_mask:0xf
	s_nop 1
	v_readlane_b32 s4, v3, 0
	v_readlane_b32 s5, v3, 16
	v_readlane_b32 s6, v3, 32
	v_readlane_b32 s7, v3, 48
	s_lshl_b32 s8, s14, 12
	s_add_u32 s10, s22, s8
	s_addc_u32 s11, s23, 0
	v_mov_b32_e32 v68, s4
	v_add_f32_e32 v68, s5, v68
	v_add_f32_e32 v68, s6, v68
	v_add_f32_e32 v68, s7, v68
	v_fmamk_f32 v68, v68, 0x3a800000, v2
	v_rsq_f32_e32 v68, v68
	s_nop 0
	v_pk_mul_f32 v[52:53], v[68:69], v[52:53] op_sel_hi:[0,1]
	v_pk_mul_f32 v[54:55], v[68:69], v[54:55] op_sel_hi:[0,1]
	v_pk_mul_f32 v[56:57], v[68:69], v[56:57] op_sel_hi:[0,1]
	v_pk_mul_f32 v[58:59], v[68:69], v[58:59] op_sel_hi:[0,1]
	v_pk_mul_f32 v[60:61], v[68:69], v[60:61] op_sel_hi:[0,1]
	v_pk_mul_f32 v[62:63], v[68:69], v[62:63] op_sel_hi:[0,1]
	v_pk_mul_f32 v[64:65], v[68:69], v[64:65] op_sel_hi:[0,1]
	v_pk_mul_f32 v[66:67], v[68:69], v[66:67] op_sel_hi:[0,1]
	v_pk_mul_f32 v[52:53], v[52:53], v[4:5]
	v_pk_mul_f32 v[54:55], v[54:55], v[6:7]
	v_pk_mul_f32 v[56:57], v[56:57], v[8:9]
	v_pk_mul_f32 v[58:59], v[58:59], v[10:11]
	v_pk_mul_f32 v[60:61], v[60:61], v[12:13]
	v_pk_mul_f32 v[62:63], v[62:63], v[14:15]
	v_pk_mul_f32 v[64:65], v[64:65], v[16:17]
	v_pk_mul_f32 v[66:67], v[66:67], v[18:19]
	global_store_dwordx4 v1, v[52:55], s[10:11] offset:0
	global_store_dwordx4 v1, v[56:59], s[10:11] offset:1024
	global_store_dwordx4 v1, v[60:63], s[10:11] offset:2048
	global_store_dwordx4 v1, v[64:67], s[10:11] offset:3072
	s_add_i32 s14, s14, s1
	s_waitcnt vmcnt(20)
	s_nop 1
	v_lshlrev_b32_e32 v52, 16, v36
	v_and_b32_e32 v53, 0xffff0000, v36
	v_lshlrev_b32_e32 v54, 16, v37
	v_and_b32_e32 v55, 0xffff0000, v37
	v_lshlrev_b32_e32 v56, 16, v38
	v_and_b32_e32 v57, 0xffff0000, v38
	v_lshlrev_b32_e32 v58, 16, v39
	v_and_b32_e32 v59, 0xffff0000, v39
	v_lshlrev_b32_e32 v60, 16, v40
	v_and_b32_e32 v61, 0xffff0000, v40
	v_lshlrev_b32_e32 v62, 16, v41
	v_and_b32_e32 v63, 0xffff0000, v41
	v_lshlrev_b32_e32 v64, 16, v42
	v_and_b32_e32 v65, 0xffff0000, v42
	v_lshlrev_b32_e32 v66, 16, v43
	v_and_b32_e32 v67, 0xffff0000, v43
	s_cmp_lt_u32 s9, 0x8400
	s_cselect_b32 s8, s9, s0
	s_lshl_b32 s8, s8, 11
	s_add_u32 s2, s12, s8
	s_addc_u32 s3, s13, 0
	global_load_dwordx2 v[36:37], v0, s[2:3] offset:0
	global_load_dwordx2 v[38:39], v0, s[2:3] offset:512
	global_load_dwordx2 v[40:41], v0, s[2:3] offset:1024
	global_load_dwordx2 v[42:43], v0, s[2:3] offset:1536
	s_add_i32 s9, s9, s1
	v_mul_f32_e32 v3, v52, v52
	v_mul_f32_e32 v70, v53, v53
	v_fmac_f32_e32 v3, v54, v54
	v_fmac_f32_e32 v70, v55, v55
	v_fmac_f32_e32 v3, v56, v56
	v_fmac_f32_e32 v70, v57, v57
	v_fmac_f32_e32 v3, v58, v58
	v_fmac_f32_e32 v70, v59, v59
	v_fmac_f32_e32 v3, v60, v60
	v_fmac_f32_e32 v70, v61, v61
	v_fmac_f32_e32 v3, v62, v62
	v_fmac_f32_e32 v70, v63, v63
	v_fmac_f32_e32 v3, v64, v64
	v_fmac_f32_e32 v70, v65, v65
	v_fmac_f32_e32 v3, v66, v66
	v_fmac_f32_e32 v70, v67, v67
	v_add_f32_e32 v3, v3, v70
	s_nop 1
	v_add_f32_dpp v3, v3, v3 quad_perm:[1,0,3,2] row_mask:0xf bank_mask:0xf
	s_nop 1
	v_add_f32_dpp v3, v3, v3 quad_perm:[2,3,0,1] row_mask:0xf bank_mask:0xf
	s_nop 1
	v_add_f32_dpp v3, v3, v3 row_half_mirror row_mask:0xf bank_mask:0xf
	s_nop 1
	v_add_f32_dpp v3, v3, v3 row_mirror row_mask:0xf bank_mask:0xf
	s_nop 1
	v_readlane_b32 s4, v3, 0
	v_readlane_b32 s5, v3, 16
	v_readlane_b32 s6, v3, 32
	v_readlane_b32 s7, v3, 48
	s_lshl_b32 s8, s14, 12
	s_add_u32 s10, s22, s8
	s_addc_u32 s11, s23, 0
	v_mov_b32_e32 v68, s4
	v_add_f32_e32 v68, s5, v68
	v_add_f32_e32 v68, s6, v68
	v_add_f32_e32 v68, s7, v68
	v_fmamk_f32 v68, v68, 0x3a800000, v2
	v_rsq_f32_e32 v68, v68
	s_nop 0
	v_pk_mul_f32 v[52:53], v[68:69], v[52:53] op_sel_hi:[0,1]
	v_pk_mul_f32 v[54:55], v[68:69], v[54:55] op_sel_hi:[0,1]
	v_pk_mul_f32 v[56:57], v[68:69], v[56:57] op_sel_hi:[0,1]
	v_pk_mul_f32 v[58:59], v[68:69], v[58:59] op_sel_hi:[0,1]
	v_pk_mul_f32 v[60:61], v[68:69], v[60:61] op_sel_hi:[0,1]
	v_pk_mul_f32 v[62:63], v[68:69], v[62:63] op_sel_hi:[0,1]
	v_pk_mul_f32 v[64:65], v[68:69], v[64:65] op_sel_hi:[0,1]
	v_pk_mul_f32 v[66:67], v[68:69], v[66:67] op_sel_hi:[0,1]
	v_pk_mul_f32 v[52:53], v[52:53], v[4:5]
	v_pk_mul_f32 v[54:55], v[54:55], v[6:7]
	v_pk_mul_f32 v[56:57], v[56:57], v[8:9]
	v_pk_mul_f32 v[58:59], v[58:59], v[10:11]
	v_pk_mul_f32 v[60:61], v[60:61], v[12:13]
	v_pk_mul_f32 v[62:63], v[62:63], v[14:15]
	v_pk_mul_f32 v[64:65], v[64:65], v[16:17]
	v_pk_mul_f32 v[66:67], v[66:67], v[18:19]
	global_store_dwordx4 v1, v[52:55], s[10:11] offset:0
	global_store_dwordx4 v1, v[56:59], s[10:11] offset:1024
	global_store_dwordx4 v1, v[60:63], s[10:11] offset:2048
	global_store_dwordx4 v1, v[64:67], s[10:11] offset:3072
	s_add_i32 s14, s14, s1
	s_waitcnt vmcnt(24)
	s_nop 1
	v_lshlrev_b32_e32 v52, 16, v44
	v_and_b32_e32 v53, 0xffff0000, v44
	v_lshlrev_b32_e32 v54, 16, v45
	v_and_b32_e32 v55, 0xffff0000, v45
	v_lshlrev_b32_e32 v56, 16, v46
	v_and_b32_e32 v57, 0xffff0000, v46
	v_lshlrev_b32_e32 v58, 16, v47
	v_and_b32_e32 v59, 0xffff0000, v47
	v_lshlrev_b32_e32 v60, 16, v48
	v_and_b32_e32 v61, 0xffff0000, v48
	v_lshlrev_b32_e32 v62, 16, v49
	v_and_b32_e32 v63, 0xffff0000, v49
	v_lshlrev_b32_e32 v64, 16, v50
	v_and_b32_e32 v65, 0xffff0000, v50
	v_lshlrev_b32_e32 v66, 16, v51
	v_and_b32_e32 v67, 0xffff0000, v51
	s_cmp_lt_u32 s9, 0x8400
	s_cselect_b32 s8, s9, s0
	s_lshl_b32 s8, s8, 11
	s_add_u32 s2, s12, s8
	s_addc_u32 s3, s13, 0
	global_load_dwordx2 v[44:45], v0, s[2:3] offset:0
	global_load_dwordx2 v[46:47], v0, s[2:3] offset:512
	global_load_dwordx2 v[48:49], v0, s[2:3] offset:1024
	global_load_dwordx2 v[50:51], v0, s[2:3] offset:1536
	s_add_i32 s9, s9, s1
	v_mul_f32_e32 v3, v52, v52
	v_mul_f32_e32 v70, v53, v53
	v_fmac_f32_e32 v3, v54, v54
	v_fmac_f32_e32 v70, v55, v55
	v_fmac_f32_e32 v3, v56, v56
	v_fmac_f32_e32 v70, v57, v57
	v_fmac_f32_e32 v3, v58, v58
	v_fmac_f32_e32 v70, v59, v59
	v_fmac_f32_e32 v3, v60, v60
	v_fmac_f32_e32 v70, v61, v61
	v_fmac_f32_e32 v3, v62, v62
	v_fmac_f32_e32 v70, v63, v63
	v_fmac_f32_e32 v3, v64, v64
	v_fmac_f32_e32 v70, v65, v65
	v_fmac_f32_e32 v3, v66, v66
	v_fmac_f32_e32 v70, v67, v67
	v_add_f32_e32 v3, v3, v70
	s_nop 1
	v_add_f32_dpp v3, v3, v3 quad_perm:[1,0,3,2] row_mask:0xf bank_mask:0xf
	s_nop 1
	v_add_f32_dpp v3, v3, v3 quad_perm:[2,3,0,1] row_mask:0xf bank_mask:0xf
	s_nop 1
	v_add_f32_dpp v3, v3, v3 row_half_mirror row_mask:0xf bank_mask:0xf
	s_nop 1
	v_add_f32_dpp v3, v3, v3 row_mirror row_mask:0xf bank_mask:0xf
	s_nop 1
	v_readlane_b32 s4, v3, 0
	v_readlane_b32 s5, v3, 16
	v_readlane_b32 s6, v3, 32
	v_readlane_b32 s7, v3, 48
	s_lshl_b32 s8, s14, 12
	s_add_u32 s10, s22, s8
	s_addc_u32 s11, s23, 0
	v_mov_b32_e32 v68, s4
	v_add_f32_e32 v68, s5, v68
	v_add_f32_e32 v68, s6, v68
	v_add_f32_e32 v68, s7, v68
	v_fmamk_f32 v68, v68, 0x3a800000, v2
	v_rsq_f32_e32 v68, v68
	s_nop 0
	v_pk_mul_f32 v[52:53], v[68:69], v[52:53] op_sel_hi:[0,1]
	v_pk_mul_f32 v[54:55], v[68:69], v[54:55] op_sel_hi:[0,1]
	v_pk_mul_f32 v[56:57], v[68:69], v[56:57] op_sel_hi:[0,1]
	v_pk_mul_f32 v[58:59], v[68:69], v[58:59] op_sel_hi:[0,1]
	v_pk_mul_f32 v[60:61], v[68:69], v[60:61] op_sel_hi:[0,1]
	v_pk_mul_f32 v[62:63], v[68:69], v[62:63] op_sel_hi:[0,1]
	v_pk_mul_f32 v[64:65], v[68:69], v[64:65] op_sel_hi:[0,1]
	v_pk_mul_f32 v[66:67], v[68:69], v[66:67] op_sel_hi:[0,1]
	v_pk_mul_f32 v[52:53], v[52:53], v[4:5]
	v_pk_mul_f32 v[54:55], v[54:55], v[6:7]
	v_pk_mul_f32 v[56:57], v[56:57], v[8:9]
	v_pk_mul_f32 v[58:59], v[58:59], v[10:11]
	v_pk_mul_f32 v[60:61], v[60:61], v[12:13]
	v_pk_mul_f32 v[62:63], v[62:63], v[14:15]
	v_pk_mul_f32 v[64:65], v[64:65], v[16:17]
	v_pk_mul_f32 v[66:67], v[66:67], v[18:19]
	global_store_dwordx4 v1, v[52:55], s[10:11] offset:0
	global_store_dwordx4 v1, v[56:59], s[10:11] offset:1024
	global_store_dwordx4 v1, v[60:63], s[10:11] offset:2048
	global_store_dwordx4 v1, v[64:67], s[10:11] offset:3072
	s_add_i32 s14, s14, s1
	s_mov_b32 s0, s14
.Lp8_loop:
	s_mul_i32 s8, s1, 3
	s_add_i32 s8, s8, s0
	s_cmp_lt_u32 s8, 0x8400
	s_cbranch_scc0 .Lp8_tail
	s_waitcnt vmcnt(28)
	s_nop 1
	v_lshlrev_b32_e32 v52, 16, v20
	v_and_b32_e32 v53, 0xffff0000, v20
	v_lshlrev_b32_e32 v54, 16, v21
	v_and_b32_e32 v55, 0xffff0000, v21
	v_lshlrev_b32_e32 v56, 16, v22
	v_and_b32_e32 v57, 0xffff0000, v22
	v_lshlrev_b32_e32 v58, 16, v23
	v_and_b32_e32 v59, 0xffff0000, v23
	v_lshlrev_b32_e32 v60, 16, v24
	v_and_b32_e32 v61, 0xffff0000, v24
	v_lshlrev_b32_e32 v62, 16, v25
	v_and_b32_e32 v63, 0xffff0000, v25
	v_lshlrev_b32_e32 v64, 16, v26
	v_and_b32_e32 v65, 0xffff0000, v26
	v_lshlrev_b32_e32 v66, 16, v27
	v_and_b32_e32 v67, 0xffff0000, v27
	s_cmp_lt_u32 s9, 0x8400
	s_cselect_b32 s8, s9, s0
	s_lshl_b32 s8, s8, 11
	s_add_u32 s2, s12, s8
	s_addc_u32 s3, s13, 0
	global_load_dwordx2 v[20:21], v0, s[2:3] offset:0
	global_load_dwordx2 v[22:23], v0, s[2:3] offset:512
	global_load_dwordx2 v[24:25], v0, s[2:3] offset:1024
	global_load_dwordx2 v[26:27], v0, s[2:3] offset:1536
	s_add_i32 s9, s9, s1
	v_mul_f32_e32 v3, v52, v52
	v_mul_f32_e32 v70, v53, v53
	v_fmac_f32_e32 v3, v54, v54
	v_fmac_f32_e32 v70, v55, v55
	v_fmac_f32_e32 v3, v56, v56
	v_fmac_f32_e32 v70, v57, v57
	v_fmac_f32_e32 v3, v58, v58
	v_fmac_f32_e32 v70, v59, v59
	v_fmac_f32_e32 v3, v60, v60
	v_fmac_f32_e32 v70, v61, v61
	v_fmac_f32_e32 v3, v62, v62
	v_fmac_f32_e32 v70, v63, v63
	v_fmac_f32_e32 v3, v64, v64
	v_fmac_f32_e32 v70, v65, v65
	v_fmac_f32_e32 v3, v66, v66
	v_fmac_f32_e32 v70, v67, v67
	v_add_f32_e32 v3, v3, v70
	s_nop 1
	v_add_f32_dpp v3, v3, v3 quad_perm:[1,0,3,2] row_mask:0xf bank_mask:0xf
	s_nop 1
	v_add_f32_dpp v3, v3, v3 quad_perm:[2,3,0,1] row_mask:0xf bank_mask:0xf
	s_nop 1
	v_add_f32_dpp v3, v3, v3 row_half_mirror row_mask:0xf bank_mask:0xf
	s_nop 1
	v_add_f32_dpp v3, v3, v3 row_mirror row_mask:0xf bank_mask:0xf
	s_nop 1
	v_readlane_b32 s4, v3, 0
	v_readlane_b32 s5, v3, 16
	v_readlane_b32 s6, v3, 32
	v_readlane_b32 s7, v3, 48
	s_lshl_b32 s8, s14, 12
	s_add_u32 s10, s22, s8
	s_addc_u32 s11, s23, 0
	v_mov_b32_e32 v68, s4
	v_add_f32_e32 v68, s5, v68
	v_add_f32_e32 v68, s6, v68
	v_add_f32_e32 v68, s7, v68
	v_fmamk_f32 v68, v68, 0x3a800000, v2
	v_rsq_f32_e32 v68, v68
	s_nop 0
	v_pk_mul_f32 v[52:53], v[68:69], v[52:53] op_sel_hi:[0,1]
	v_pk_mul_f32 v[54:55], v[68:69], v[54:55] op_sel_hi:[0,1]
	v_pk_mul_f32 v[56:57], v[68:69], v[56:57] op_sel_hi:[0,1]
	v_pk_mul_f32 v[58:59], v[68:69], v[58:59] op_sel_hi:[0,1]
	v_pk_mul_f32 v[60:61], v[68:69], v[60:61] op_sel_hi:[0,1]
	v_pk_mul_f32 v[62:63], v[68:69], v[62:63] op_sel_hi:[0,1]
	v_pk_mul_f32 v[64:65], v[68:69], v[64:65] op_sel_hi:[0,1]
	v_pk_mul_f32 v[66:67], v[68:69], v[66:67] op_sel_hi:[0,1]
	v_pk_mul_f32 v[52:53], v[52:53], v[4:5]
	v_pk_mul_f32 v[54:55], v[54:55], v[6:7]
	v_pk_mul_f32 v[56:57], v[56:57], v[8:9]
	v_pk_mul_f32 v[58:59], v[58:59], v[10:11]
	v_pk_mul_f32 v[60:61], v[60:61], v[12:13]
	v_pk_mul_f32 v[62:63], v[62:63], v[14:15]
	v_pk_mul_f32 v[64:65], v[64:65], v[16:17]
	v_pk_mul_f32 v[66:67], v[66:67], v[18:19]
	global_store_dwordx4 v1, v[52:55], s[10:11] offset:0
	global_store_dwordx4 v1, v[56:59], s[10:11] offset:1024
	global_store_dwordx4 v1, v[60:63], s[10:11] offset:2048
	global_store_dwordx4 v1, v[64:67], s[10:11] offset:3072
	s_add_i32 s14, s14, s1
	s_waitcnt vmcnt(28)
	s_nop 1
	v_lshlrev_b32_e32 v52, 16, v28
	v_and_b32_e32 v53, 0xffff0000, v28
	v_lshlrev_b32_e32 v54, 16, v29
	v_and_b32_e32 v55, 0xffff0000, v29
	v_lshlrev_b32_e32 v56, 16, v30
	v_and_b32_e32 v57, 0xffff0000, v30
	v_lshlrev_b32_e32 v58, 16, v31
	v_and_b32_e32 v59, 0xffff0000, v31
	v_lshlrev_b32_e32 v60, 16, v32
	v_and_b32_e32 v61, 0xffff0000, v32
	v_lshlrev_b32_e32 v62, 16, v33
	v_and_b32_e32 v63, 0xffff0000, v33
	v_lshlrev_b32_e32 v64, 16, v34
	v_and_b32_e32 v65, 0xffff0000, v34
	v_lshlrev_b32_e32 v66, 16, v35
	v_and_b32_e32 v67, 0xffff0000, v35
	s_cmp_lt_u32 s9, 0x8400
	s_cselect_b32 s8, s9, s0
	s_lshl_b32 s8, s8, 11
	s_add_u32 s2, s12, s8
	s_addc_u32 s3, s13, 0
	global_load_dwordx2 v[28:29], v0, s[2:3] offset:0
	global_load_dwordx2 v[30:31], v0, s[2:3] offset:512
	global_load_dwordx2 v[32:33], v0, s[2:3] offset:1024
	global_load_dwordx2 v[34:35], v0, s[2:3] offset:1536
	s_add_i32 s9, s9, s1
	v_mul_f32_e32 v3, v52, v52
	v_mul_f32_e32 v70, v53, v53
	v_fmac_f32_e32 v3, v54, v54
	v_fmac_f32_e32 v70, v55, v55
	v_fmac_f32_e32 v3, v56, v56
	v_fmac_f32_e32 v70, v57, v57
	v_fmac_f32_e32 v3, v58, v58
	v_fmac_f32_e32 v70, v59, v59
	v_fmac_f32_e32 v3, v60, v60
	v_fmac_f32_e32 v70, v61, v61
	v_fmac_f32_e32 v3, v62, v62
	v_fmac_f32_e32 v70, v63, v63
	v_fmac_f32_e32 v3, v64, v64
	v_fmac_f32_e32 v70, v65, v65
	v_fmac_f32_e32 v3, v66, v66
	v_fmac_f32_e32 v70, v67, v67
	v_add_f32_e32 v3, v3, v70
	s_nop 1
	v_add_f32_dpp v3, v3, v3 quad_perm:[1,0,3,2] row_mask:0xf bank_mask:0xf
	s_nop 1
	v_add_f32_dpp v3, v3, v3 quad_perm:[2,3,0,1] row_mask:0xf bank_mask:0xf
	s_nop 1
	v_add_f32_dpp v3, v3, v3 row_half_mirror row_mask:0xf bank_mask:0xf
	s_nop 1
	v_add_f32_dpp v3, v3, v3 row_mirror row_mask:0xf bank_mask:0xf
	s_nop 1
	v_readlane_b32 s4, v3, 0
	v_readlane_b32 s5, v3, 16
	v_readlane_b32 s6, v3, 32
	v_readlane_b32 s7, v3, 48
	s_lshl_b32 s8, s14, 12
	s_add_u32 s10, s22, s8
	s_addc_u32 s11, s23, 0
	v_mov_b32_e32 v68, s4
	v_add_f32_e32 v68, s5, v68
	v_add_f32_e32 v68, s6, v68
	v_add_f32_e32 v68, s7, v68
	v_fmamk_f32 v68, v68, 0x3a800000, v2
	v_rsq_f32_e32 v68, v68
	s_nop 0
	v_pk_mul_f32 v[52:53], v[68:69], v[52:53] op_sel_hi:[0,1]
	v_pk_mul_f32 v[54:55], v[68:69], v[54:55] op_sel_hi:[0,1]
	v_pk_mul_f32 v[56:57], v[68:69], v[56:57] op_sel_hi:[0,1]
	v_pk_mul_f32 v[58:59], v[68:69], v[58:59] op_sel_hi:[0,1]
	v_pk_mul_f32 v[60:61], v[68:69], v[60:61] op_sel_hi:[0,1]
	v_pk_mul_f32 v[62:63], v[68:69], v[62:63] op_sel_hi:[0,1]
	v_pk_mul_f32 v[64:65], v[68:69], v[64:65] op_sel_hi:[0,1]
	v_pk_mul_f32 v[66:67], v[68:69], v[66:67] op_sel_hi:[0,1]
	v_pk_mul_f32 v[52:53], v[52:53], v[4:5]
	v_pk_mul_f32 v[54:55], v[54:55], v[6:7]
	v_pk_mul_f32 v[56:57], v[56:57], v[8:9]
	v_pk_mul_f32 v[58:59], v[58:59], v[10:11]
	v_pk_mul_f32 v[60:61], v[60:61], v[12:13]
	v_pk_mul_f32 v[62:63], v[62:63], v[14:15]
	v_pk_mul_f32 v[64:65], v[64:65], v[16:17]
	v_pk_mul_f32 v[66:67], v[66:67], v[18:19]
	global_store_dwordx4 v1, v[52:55], s[10:11] offset:0
	global_store_dwordx4 v1, v[56:59], s[10:11] offset:1024
	global_store_dwordx4 v1, v[60:63], s[10:11] offset:2048
	global_store_dwordx4 v1, v[64:67], s[10:11] offset:3072
	s_add_i32 s14, s14, s1
	s_waitcnt vmcnt(28)
	s_nop 1
	v_lshlrev_b32_e32 v52, 16, v36
	v_and_b32_e32 v53, 0xffff0000, v36
	v_lshlrev_b32_e32 v54, 16, v37
	v_and_b32_e32 v55, 0xffff0000, v37
	v_lshlrev_b32_e32 v56, 16, v38
	v_and_b32_e32 v57, 0xffff0000, v38
	v_lshlrev_b32_e32 v58, 16, v39
	v_and_b32_e32 v59, 0xffff0000, v39
	v_lshlrev_b32_e32 v60, 16, v40
	v_and_b32_e32 v61, 0xffff0000, v40
	v_lshlrev_b32_e32 v62, 16, v41
	v_and_b32_e32 v63, 0xffff0000, v41
	v_lshlrev_b32_e32 v64, 16, v42
	v_and_b32_e32 v65, 0xffff0000, v42
	v_lshlrev_b32_e32 v66, 16, v43
	v_and_b32_e32 v67, 0xffff0000, v43
	s_cmp_lt_u32 s9, 0x8400
	s_cselect_b32 s8, s9, s0
	s_lshl_b32 s8, s8, 11
	s_add_u32 s2, s12, s8
	s_addc_u32 s3, s13, 0
	global_load_dwordx2 v[36:37], v0, s[2:3] offset:0
	global_load_dwordx2 v[38:39], v0, s[2:3] offset:512
	global_load_dwordx2 v[40:41], v0, s[2:3] offset:1024
	global_load_dwordx2 v[42:43], v0, s[2:3] offset:1536
	s_add_i32 s9, s9, s1
	v_mul_f32_e32 v3, v52, v52
	v_mul_f32_e32 v70, v53, v53
	v_fmac_f32_e32 v3, v54, v54
	v_fmac_f32_e32 v70, v55, v55
	v_fmac_f32_e32 v3, v56, v56
	v_fmac_f32_e32 v70, v57, v57
	v_fmac_f32_e32 v3, v58, v58
	v_fmac_f32_e32 v70, v59, v59
	v_fmac_f32_e32 v3, v60, v60
	v_fmac_f32_e32 v70, v61, v61
	v_fmac_f32_e32 v3, v62, v62
	v_fmac_f32_e32 v70, v63, v63
	v_fmac_f32_e32 v3, v64, v64
	v_fmac_f32_e32 v70, v65, v65
	v_fmac_f32_e32 v3, v66, v66
	v_fmac_f32_e32 v70, v67, v67
	v_add_f32_e32 v3, v3, v70
	s_nop 1
	v_add_f32_dpp v3, v3, v3 quad_perm:[1,0,3,2] row_mask:0xf bank_mask:0xf
	s_nop 1
	v_add_f32_dpp v3, v3, v3 quad_perm:[2,3,0,1] row_mask:0xf bank_mask:0xf
	s_nop 1
	v_add_f32_dpp v3, v3, v3 row_half_mirror row_mask:0xf bank_mask:0xf
	s_nop 1
	v_add_f32_dpp v3, v3, v3 row_mirror row_mask:0xf bank_mask:0xf
	s_nop 1
	v_readlane_b32 s4, v3, 0
	v_readlane_b32 s5, v3, 16
	v_readlane_b32 s6, v3, 32
	v_readlane_b32 s7, v3, 48
	s_lshl_b32 s8, s14, 12
	s_add_u32 s10, s22, s8
	s_addc_u32 s11, s23, 0
	v_mov_b32_e32 v68, s4
	v_add_f32_e32 v68, s5, v68
	v_add_f32_e32 v68, s6, v68
	v_add_f32_e32 v68, s7, v68
	v_fmamk_f32 v68, v68, 0x3a800000, v2
	v_rsq_f32_e32 v68, v68
	s_nop 0
	v_pk_mul_f32 v[52:53], v[68:69], v[52:53] op_sel_hi:[0,1]
	v_pk_mul_f32 v[54:55], v[68:69], v[54:55] op_sel_hi:[0,1]
	v_pk_mul_f32 v[56:57], v[68:69], v[56:57] op_sel_hi:[0,1]
	v_pk_mul_f32 v[58:59], v[68:69], v[58:59] op_sel_hi:[0,1]
	v_pk_mul_f32 v[60:61], v[68:69], v[60:61] op_sel_hi:[0,1]
	v_pk_mul_f32 v[62:63], v[68:69], v[62:63] op_sel_hi:[0,1]
	v_pk_mul_f32 v[64:65], v[68:69], v[64:65] op_sel_hi:[0,1]
	v_pk_mul_f32 v[66:67], v[68:69], v[66:67] op_sel_hi:[0,1]
	v_pk_mul_f32 v[52:53], v[52:53], v[4:5]
	v_pk_mul_f32 v[54:55], v[54:55], v[6:7]
	v_pk_mul_f32 v[56:57], v[56:57], v[8:9]
	v_pk_mul_f32 v[58:59], v[58:59], v[10:11]
	v_pk_mul_f32 v[60:61], v[60:61], v[12:13]
	v_pk_mul_f32 v[62:63], v[62:63], v[14:15]
	v_pk_mul_f32 v[64:65], v[64:65], v[16:17]
	v_pk_mul_f32 v[66:67], v[66:67], v[18:19]
	global_store_dwordx4 v1, v[52:55], s[10:11] offset:0
	global_store_dwordx4 v1, v[56:59], s[10:11] offset:1024
	global_store_dwordx4 v1, v[60:63], s[10:11] offset:2048
	global_store_dwordx4 v1, v[64:67], s[10:11] offset:3072
	s_add_i32 s14, s14, s1
	s_waitcnt vmcnt(28)
	s_nop 1
	v_lshlrev_b32_e32 v52, 16, v44
	v_and_b32_e32 v53, 0xffff0000, v44
	v_lshlrev_b32_e32 v54, 16, v45
	v_and_b32_e32 v55, 0xffff0000, v45
	v_lshlrev_b32_e32 v56, 16, v46
	v_and_b32_e32 v57, 0xffff0000, v46
	v_lshlrev_b32_e32 v58, 16, v47
	v_and_b32_e32 v59, 0xffff0000, v47
	v_lshlrev_b32_e32 v60, 16, v48
	v_and_b32_e32 v61, 0xffff0000, v48
	v_lshlrev_b32_e32 v62, 16, v49
	v_and_b32_e32 v63, 0xffff0000, v49
	v_lshlrev_b32_e32 v64, 16, v50
	v_and_b32_e32 v65, 0xffff0000, v50
	v_lshlrev_b32_e32 v66, 16, v51
	v_and_b32_e32 v67, 0xffff0000, v51
	s_cmp_lt_u32 s9, 0x8400
	s_cselect_b32 s8, s9, s0
	s_lshl_b32 s8, s8, 11
	s_add_u32 s2, s12, s8
	s_addc_u32 s3, s13, 0
	global_load_dwordx2 v[44:45], v0, s[2:3] offset:0
	global_load_dwordx2 v[46:47], v0, s[2:3] offset:512
	global_load_dwordx2 v[48:49], v0, s[2:3] offset:1024
	global_load_dwordx2 v[50:51], v0, s[2:3] offset:1536
	s_add_i32 s9, s9, s1
	v_mul_f32_e32 v3, v52, v52
	v_mul_f32_e32 v70, v53, v53
	v_fmac_f32_e32 v3, v54, v54
	v_fmac_f32_e32 v70, v55, v55
	v_fmac_f32_e32 v3, v56, v56
	v_fmac_f32_e32 v70, v57, v57
	v_fmac_f32_e32 v3, v58, v58
	v_fmac_f32_e32 v70, v59, v59
	v_fmac_f32_e32 v3, v60, v60
	v_fmac_f32_e32 v70, v61, v61
	v_fmac_f32_e32 v3, v62, v62
	v_fmac_f32_e32 v70, v63, v63
	v_fmac_f32_e32 v3, v64, v64
	v_fmac_f32_e32 v70, v65, v65
	v_fmac_f32_e32 v3, v66, v66
	v_fmac_f32_e32 v70, v67, v67
	v_add_f32_e32 v3, v3, v70
	s_nop 1
	v_add_f32_dpp v3, v3, v3 quad_perm:[1,0,3,2] row_mask:0xf bank_mask:0xf
	s_nop 1
	v_add_f32_dpp v3, v3, v3 quad_perm:[2,3,0,1] row_mask:0xf bank_mask:0xf
	s_nop 1
	v_add_f32_dpp v3, v3, v3 row_half_mirror row_mask:0xf bank_mask:0xf
	s_nop 1
	v_add_f32_dpp v3, v3, v3 row_mirror row_mask:0xf bank_mask:0xf
	s_nop 1
	v_readlane_b32 s4, v3, 0
	v_readlane_b32 s5, v3, 16
	v_readlane_b32 s6, v3, 32
	v_readlane_b32 s7, v3, 48
	s_lshl_b32 s8, s14, 12
	s_add_u32 s10, s22, s8
	s_addc_u32 s11, s23, 0
	v_mov_b32_e32 v68, s4
	v_add_f32_e32 v68, s5, v68
	v_add_f32_e32 v68, s6, v68
	v_add_f32_e32 v68, s7, v68
	v_fmamk_f32 v68, v68, 0x3a800000, v2
	v_rsq_f32_e32 v68, v68
	s_nop 0
	v_pk_mul_f32 v[52:53], v[68:69], v[52:53] op_sel_hi:[0,1]
	v_pk_mul_f32 v[54:55], v[68:69], v[54:55] op_sel_hi:[0,1]
	v_pk_mul_f32 v[56:57], v[68:69], v[56:57] op_sel_hi:[0,1]
	v_pk_mul_f32 v[58:59], v[68:69], v[58:59] op_sel_hi:[0,1]
	v_pk_mul_f32 v[60:61], v[68:69], v[60:61] op_sel_hi:[0,1]
	v_pk_mul_f32 v[62:63], v[68:69], v[62:63] op_sel_hi:[0,1]
	v_pk_mul_f32 v[64:65], v[68:69], v[64:65] op_sel_hi:[0,1]
	v_pk_mul_f32 v[66:67], v[68:69], v[66:67] op_sel_hi:[0,1]
	v_pk_mul_f32 v[52:53], v[52:53], v[4:5]
	v_pk_mul_f32 v[54:55], v[54:55], v[6:7]
	v_pk_mul_f32 v[56:57], v[56:57], v[8:9]
	v_pk_mul_f32 v[58:59], v[58:59], v[10:11]
	v_pk_mul_f32 v[60:61], v[60:61], v[12:13]
	v_pk_mul_f32 v[62:63], v[62:63], v[14:15]
	v_pk_mul_f32 v[64:65], v[64:65], v[16:17]
	v_pk_mul_f32 v[66:67], v[66:67], v[18:19]
	global_store_dwordx4 v1, v[52:55], s[10:11] offset:0
	global_store_dwordx4 v1, v[56:59], s[10:11] offset:1024
	global_store_dwordx4 v1, v[60:63], s[10:11] offset:2048
	global_store_dwordx4 v1, v[64:67], s[10:11] offset:3072
	s_add_i32 s14, s14, s1
	s_mov_b32 s0, s14
	s_branch .Lp8_loop
.Lp8_tail:
	s_waitcnt vmcnt(0)
	s_mov_b32 s14, s0
	s_cmp_lt_u32 s14, 0x8400
	s_cbranch_scc0 .Lp8_done
	s_nop 1
	v_lshlrev_b32_e32 v52, 16, v20
	v_and_b32_e32 v53, 0xffff0000, v20
	v_lshlrev_b32_e32 v54, 16, v21
	v_and_b32_e32 v55, 0xffff0000, v21
	v_lshlrev_b32_e32 v56, 16, v22
	v_and_b32_e32 v57, 0xffff0000, v22
	v_lshlrev_b32_e32 v58, 16, v23
	v_and_b32_e32 v59, 0xffff0000, v23
	v_lshlrev_b32_e32 v60, 16, v24
	v_and_b32_e32 v61, 0xffff0000, v24
	v_lshlrev_b32_e32 v62, 16, v25
	v_and_b32_e32 v63, 0xffff0000, v25
	v_lshlrev_b32_e32 v64, 16, v26
	v_and_b32_e32 v65, 0xffff0000, v26
	v_lshlrev_b32_e32 v66, 16, v27
	v_and_b32_e32 v67, 0xffff0000, v27
	v_mul_f32_e32 v3, v52, v52
	v_mul_f32_e32 v70, v53, v53
	v_fmac_f32_e32 v3, v54, v54
	v_fmac_f32_e32 v70, v55, v55
	v_fmac_f32_e32 v3, v56, v56
	v_fmac_f32_e32 v70, v57, v57
	v_fmac_f32_e32 v3, v58, v58
	v_fmac_f32_e32 v70, v59, v59
	v_fmac_f32_e32 v3, v60, v60
	v_fmac_f32_e32 v70, v61, v61
	v_fmac_f32_e32 v3, v62, v62
	v_fmac_f32_e32 v70, v63, v63
	v_fmac_f32_e32 v3, v64, v64
	v_fmac_f32_e32 v70, v65, v65
	v_fmac_f32_e32 v3, v66, v66
	v_fmac_f32_e32 v70, v67, v67
	v_add_f32_e32 v3, v3, v70
	s_nop 1
	v_add_f32_dpp v3, v3, v3 quad_perm:[1,0,3,2] row_mask:0xf bank_mask:0xf
	s_nop 1
	v_add_f32_dpp v3, v3, v3 quad_perm:[2,3,0,1] row_mask:0xf bank_mask:0xf
	s_nop 1
	v_add_f32_dpp v3, v3, v3 row_half_mirror row_mask:0xf bank_mask:0xf
	s_nop 1
	v_add_f32_dpp v3, v3, v3 row_mirror row_mask:0xf bank_mask:0xf
	s_nop 1
	v_readlane_b32 s4, v3, 0
	v_readlane_b32 s5, v3, 16
	v_readlane_b32 s6, v3, 32
	v_readlane_b32 s7, v3, 48
	s_lshl_b32 s8, s14, 12
	s_add_u32 s10, s22, s8
	s_addc_u32 s11, s23, 0
	v_mov_b32_e32 v68, s4
	v_add_f32_e32 v68, s5, v68
	v_add_f32_e32 v68, s6, v68
	v_add_f32_e32 v68, s7, v68
	v_fmamk_f32 v68, v68, 0x3a800000, v2
	v_rsq_f32_e32 v68, v68
	s_nop 0
	v_pk_mul_f32 v[52:53], v[68:69], v[52:53] op_sel_hi:[0,1]
	v_pk_mul_f32 v[54:55], v[68:69], v[54:55] op_sel_hi:[0,1]
	v_pk_mul_f32 v[56:57], v[68:69], v[56:57] op_sel_hi:[0,1]
	v_pk_mul_f32 v[58:59], v[68:69], v[58:59] op_sel_hi:[0,1]
	v_pk_mul_f32 v[60:61], v[68:69], v[60:61] op_sel_hi:[0,1]
	v_pk_mul_f32 v[62:63], v[68:69], v[62:63] op_sel_hi:[0,1]
	v_pk_mul_f32 v[64:65], v[68:69], v[64:65] op_sel_hi:[0,1]
	v_pk_mul_f32 v[66:67], v[68:69], v[66:67] op_sel_hi:[0,1]
	v_pk_mul_f32 v[52:53], v[52:53], v[4:5]
	v_pk_mul_f32 v[54:55], v[54:55], v[6:7]
	v_pk_mul_f32 v[56:57], v[56:57], v[8:9]
	v_pk_mul_f32 v[58:59], v[58:59], v[10:11]
	v_pk_mul_f32 v[60:61], v[60:61], v[12:13]
	v_pk_mul_f32 v[62:63], v[62:63], v[14:15]
	v_pk_mul_f32 v[64:65], v[64:65], v[16:17]
	v_pk_mul_f32 v[66:67], v[66:67], v[18:19]
	global_store_dwordx4 v1, v[52:55], s[10:11] offset:0
	global_store_dwordx4 v1, v[56:59], s[10:11] offset:1024
	global_store_dwordx4 v1, v[60:63], s[10:11] offset:2048
	global_store_dwordx4 v1, v[64:67], s[10:11] offset:3072
	s_add_i32 s14, s14, s1
	s_cmp_lt_u32 s14, 0x8400
	s_cbranch_scc0 .Lp8_done
	s_nop 1
	v_lshlrev_b32_e32 v52, 16, v28
	v_and_b32_e32 v53, 0xffff0000, v28
	v_lshlrev_b32_e32 v54, 16, v29
	v_and_b32_e32 v55, 0xffff0000, v29
	v_lshlrev_b32_e32 v56, 16, v30
	v_and_b32_e32 v57, 0xffff0000, v30
	v_lshlrev_b32_e32 v58, 16, v31
	v_and_b32_e32 v59, 0xffff0000, v31
	v_lshlrev_b32_e32 v60, 16, v32
	v_and_b32_e32 v61, 0xffff0000, v32
	v_lshlrev_b32_e32 v62, 16, v33
	v_and_b32_e32 v63, 0xffff0000, v33
	v_lshlrev_b32_e32 v64, 16, v34
	v_and_b32_e32 v65, 0xffff0000, v34
	v_lshlrev_b32_e32 v66, 16, v35
	v_and_b32_e32 v67, 0xffff0000, v35
	v_mul_f32_e32 v3, v52, v52
	v_mul_f32_e32 v70, v53, v53
	v_fmac_f32_e32 v3, v54, v54
	v_fmac_f32_e32 v70, v55, v55
	v_fmac_f32_e32 v3, v56, v56
	v_fmac_f32_e32 v70, v57, v57
	v_fmac_f32_e32 v3, v58, v58
	v_fmac_f32_e32 v70, v59, v59
	v_fmac_f32_e32 v3, v60, v60
	v_fmac_f32_e32 v70, v61, v61
	v_fmac_f32_e32 v3, v62, v62
	v_fmac_f32_e32 v70, v63, v63
	v_fmac_f32_e32 v3, v64, v64
	v_fmac_f32_e32 v70, v65, v65
	v_fmac_f32_e32 v3, v66, v66
	v_fmac_f32_e32 v70, v67, v67
	v_add_f32_e32 v3, v3, v70
	s_nop 1
	v_add_f32_dpp v3, v3, v3 quad_perm:[1,0,3,2] row_mask:0xf bank_mask:0xf
	s_nop 1
	v_add_f32_dpp v3, v3, v3 quad_perm:[2,3,0,1] row_mask:0xf bank_mask:0xf
	s_nop 1
	v_add_f32_dpp v3, v3, v3 row_half_mirror row_mask:0xf bank_mask:0xf
	s_nop 1
	v_add_f32_dpp v3, v3, v3 row_mirror row_mask:0xf bank_mask:0xf
	s_nop 1
	v_readlane_b32 s4, v3, 0
	v_readlane_b32 s5, v3, 16
	v_readlane_b32 s6, v3, 32
	v_readlane_b32 s7, v3, 48
	s_lshl_b32 s8, s14, 12
	s_add_u32 s10, s22, s8
	s_addc_u32 s11, s23, 0
	v_mov_b32_e32 v68, s4
	v_add_f32_e32 v68, s5, v68
	v_add_f32_e32 v68, s6, v68
	v_add_f32_e32 v68, s7, v68
	v_fmamk_f32 v68, v68, 0x3a800000, v2
	v_rsq_f32_e32 v68, v68
	s_nop 0
	v_pk_mul_f32 v[52:53], v[68:69], v[52:53] op_sel_hi:[0,1]
	v_pk_mul_f32 v[54:55], v[68:69], v[54:55] op_sel_hi:[0,1]
	v_pk_mul_f32 v[56:57], v[68:69], v[56:57] op_sel_hi:[0,1]
	v_pk_mul_f32 v[58:59], v[68:69], v[58:59] op_sel_hi:[0,1]
	v_pk_mul_f32 v[60:61], v[68:69], v[60:61] op_sel_hi:[0,1]
	v_pk_mul_f32 v[62:63], v[68:69], v[62:63] op_sel_hi:[0,1]
	v_pk_mul_f32 v[64:65], v[68:69], v[64:65] op_sel_hi:[0,1]
	v_pk_mul_f32 v[66:67], v[68:69], v[66:67] op_sel_hi:[0,1]
	v_pk_mul_f32 v[52:53], v[52:53], v[4:5]
	v_pk_mul_f32 v[54:55], v[54:55], v[6:7]
	v_pk_mul_f32 v[56:57], v[56:57], v[8:9]
	v_pk_mul_f32 v[58:59], v[58:59], v[10:11]
	v_pk_mul_f32 v[60:61], v[60:61], v[12:13]
	v_pk_mul_f32 v[62:63], v[62:63], v[14:15]
	v_pk_mul_f32 v[64:65], v[64:65], v[16:17]
	v_pk_mul_f32 v[66:67], v[66:67], v[18:19]
	global_store_dwordx4 v1, v[52:55], s[10:11] offset:0
	global_store_dwordx4 v1, v[56:59], s[10:11] offset:1024
	global_store_dwordx4 v1, v[60:63], s[10:11] offset:2048
	global_store_dwordx4 v1, v[64:67], s[10:11] offset:3072
	s_add_i32 s14, s14, s1
	s_cmp_lt_u32 s14, 0x8400
	s_cbranch_scc0 .Lp8_done
	s_nop 1
	v_lshlrev_b32_e32 v52, 16, v36
	v_and_b32_e32 v53, 0xffff0000, v36
	v_lshlrev_b32_e32 v54, 16, v37
	v_and_b32_e32 v55, 0xffff0000, v37
	v_lshlrev_b32_e32 v56, 16, v38
	v_and_b32_e32 v57, 0xffff0000, v38
	v_lshlrev_b32_e32 v58, 16, v39
	v_and_b32_e32 v59, 0xffff0000, v39
	v_lshlrev_b32_e32 v60, 16, v40
	v_and_b32_e32 v61, 0xffff0000, v40
	v_lshlrev_b32_e32 v62, 16, v41
	v_and_b32_e32 v63, 0xffff0000, v41
	v_lshlrev_b32_e32 v64, 16, v42
	v_and_b32_e32 v65, 0xffff0000, v42
	v_lshlrev_b32_e32 v66, 16, v43
	v_and_b32_e32 v67, 0xffff0000, v43
	v_mul_f32_e32 v3, v52, v52
	v_mul_f32_e32 v70, v53, v53
	v_fmac_f32_e32 v3, v54, v54
	v_fmac_f32_e32 v70, v55, v55
	v_fmac_f32_e32 v3, v56, v56
	v_fmac_f32_e32 v70, v57, v57
	v_fmac_f32_e32 v3, v58, v58
	v_fmac_f32_e32 v70, v59, v59
	v_fmac_f32_e32 v3, v60, v60
	v_fmac_f32_e32 v70, v61, v61
	v_fmac_f32_e32 v3, v62, v62
	v_fmac_f32_e32 v70, v63, v63
	v_fmac_f32_e32 v3, v64, v64
	v_fmac_f32_e32 v70, v65, v65
	v_fmac_f32_e32 v3, v66, v66
	v_fmac_f32_e32 v70, v67, v67
	v_add_f32_e32 v3, v3, v70
	s_nop 1
	v_add_f32_dpp v3, v3, v3 quad_perm:[1,0,3,2] row_mask:0xf bank_mask:0xf
	s_nop 1
	v_add_f32_dpp v3, v3, v3 quad_perm:[2,3,0,1] row_mask:0xf bank_mask:0xf
	s_nop 1
	v_add_f32_dpp v3, v3, v3 row_half_mirror row_mask:0xf bank_mask:0xf
	s_nop 1
	v_add_f32_dpp v3, v3, v3 row_mirror row_mask:0xf bank_mask:0xf
	s_nop 1
	v_readlane_b32 s4, v3, 0
	v_readlane_b32 s5, v3, 16
	v_readlane_b32 s6, v3, 32
	v_readlane_b32 s7, v3, 48
	s_lshl_b32 s8, s14, 12
	s_add_u32 s10, s22, s8
	s_addc_u32 s11, s23, 0
	v_mov_b32_e32 v68, s4
	v_add_f32_e32 v68, s5, v68
	v_add_f32_e32 v68, s6, v68
	v_add_f32_e32 v68, s7, v68
	v_fmamk_f32 v68, v68, 0x3a800000, v2
	v_rsq_f32_e32 v68, v68
	s_nop 0
	v_pk_mul_f32 v[52:53], v[68:69], v[52:53] op_sel_hi:[0,1]
	v_pk_mul_f32 v[54:55], v[68:69], v[54:55] op_sel_hi:[0,1]
	v_pk_mul_f32 v[56:57], v[68:69], v[56:57] op_sel_hi:[0,1]
	v_pk_mul_f32 v[58:59], v[68:69], v[58:59] op_sel_hi:[0,1]
	v_pk_mul_f32 v[60:61], v[68:69], v[60:61] op_sel_hi:[0,1]
	v_pk_mul_f32 v[62:63], v[68:69], v[62:63] op_sel_hi:[0,1]
	v_pk_mul_f32 v[64:65], v[68:69], v[64:65] op_sel_hi:[0,1]
	v_pk_mul_f32 v[66:67], v[68:69], v[66:67] op_sel_hi:[0,1]
	v_pk_mul_f32 v[52:53], v[52:53], v[4:5]
	v_pk_mul_f32 v[54:55], v[54:55], v[6:7]
	v_pk_mul_f32 v[56:57], v[56:57], v[8:9]
	v_pk_mul_f32 v[58:59], v[58:59], v[10:11]
	v_pk_mul_f32 v[60:61], v[60:61], v[12:13]
	v_pk_mul_f32 v[62:63], v[62:63], v[14:15]
	v_pk_mul_f32 v[64:65], v[64:65], v[16:17]
	v_pk_mul_f32 v[66:67], v[66:67], v[18:19]
	global_store_dwordx4 v1, v[52:55], s[10:11] offset:0
	global_store_dwordx4 v1, v[56:59], s[10:11] offset:1024
	global_store_dwordx4 v1, v[60:63], s[10:11] offset:2048
	global_store_dwordx4 v1, v[64:67], s[10:11] offset:3072
	s_add_i32 s14, s14, s1
.Lp8_done:
.LBB0_1214:
	s_endpgm
